# EpiRes epilogues: next step LDS writes issued before the current step compute (software pipelining)
# baseline (speedup 1.0000x reference)
.LBB0_1439:
	v_and_b32_e32 v128, 63, v180
	v_and_b32_e32 v129, 15, v180
	v_bfe_u32 v130, v180, 4, 2
	v_lshrrev_b32_e32 v131, 6, v180
	v_lshlrev_b32_e32 v131, 12, v131
	v_add_u32_e32 v131, 0x20000, v131
	v_and_b32_e32 v132, 7, v129
	v_xor_b32_e32 v132, v130, v132
	v_lshlrev_b32_e32 v132, 4, v132
	v_lshl_add_u32 v132, v129, 8, v132
	v_add_u32_e32 v169, v131, v132
	v_xor_b32_e32 v170, 64, v169
	v_lshrrev_b32_e32 v133, 2, v128
	v_and_b32_e32 v134, 3, v128
	v_and_b32_e32 v135, 7, v133
	v_lshlrev_b32_e32 v136, 1, v134
	v_xor_b32_e32 v136, v136, v135
	v_lshlrev_b32_e32 v136, 4, v136
	v_lshl_add_u32 v136, v133, 8, v136
	v_add_u32_e32 v171, v131, v136
	v_xor_b32_e32 v172, 16, v171
	s_lshl_b32 s9, s34, 20
	s_cmp_lt_u32 s34, 0x100
	s_cselect_b32 s98, s12, s14
	s_cselect_b32 s99, s13, s15
	s_cselect_b32 s9, s9, 0
	s_add_u32 s98, s98, s9
	s_addc_u32 s99, s99, 0
	v_add_u32_e32 v137, s54, v133
	v_lshlrev_b32_e32 v137, 12, v137
	s_lshl_b32 s9, s8, 8
	s_add_i32 s9, s9, s55
	v_lshl_add_u32 v138, v134, 3, s9
	v_lshl_add_u32 v175, v138, 2, v137
	s_lshl_b32 s9, s34, 8
	s_add_i32 s9, s9, s54
	v_add_u32_e32 v139, s9, v133
	v_lshlrev_b32_e32 v174, 2, v139
	v_lshlrev_b32_e32 v139, 11, v139
	v_lshl_add_u32 v173, v138, 1, v139
	v_cmp_eq_u32_e32 vcc, 0, v134
	global_load_dwordx4 v[188:191], v175, s[98:99]
	global_load_dwordx4 v[192:195], v175, s[98:99] offset:16
	global_load_dwordx4 v[196:199], v175, s[98:99] offset:512
	global_load_dwordx4 v[200:203], v175, s[98:99] offset:528
	s_add_u32 s98, s98, 0x10000
	s_addc_u32 s99, s99, 0
	global_load_dwordx4 v[204:207], v175, s[98:99]
	global_load_dwordx4 v[208:211], v175, s[98:99] offset:16
	global_load_dwordx4 v[212:215], v175, s[98:99] offset:512
	global_load_dwordx4 v[216:219], v175, s[98:99] offset:528
	s_add_u32 s98, s98, 0x10000
	s_addc_u32 s99, s99, 0
	global_load_dwordx4 v[220:223], v175, s[98:99]
	global_load_dwordx4 v[224:227], v175, s[98:99] offset:16
	global_load_dwordx4 v[228:231], v175, s[98:99] offset:512
	global_load_dwordx4 v[232:235], v175, s[98:99] offset:528
	s_add_u32 s98, s98, 0x10000
	s_addc_u32 s99, s99, 0
	global_load_dwordx4 v[236:239], v175, s[98:99]
	global_load_dwordx4 v[240:243], v175, s[98:99] offset:16
	global_load_dwordx4 v[244:247], v175, s[98:99] offset:512
	global_load_dwordx4 v[248:251], v175, s[98:99] offset:528
	s_add_u32 s98, s98, 0x50000
	s_addc_u32 s99, s99, 0
	s_mov_b64 s[8:9], exec
	ds_write_b128 v169, v[124:127]
	ds_write_b128 v170, v[120:123]
	ds_write_b128 v169, v[116:119] offset:128
	ds_write_b128 v170, v[112:115] offset:128
	s_waitcnt lgkmcnt(0)
	ds_read_b128 v[128:131], v171
	ds_read_b128 v[132:135], v172
	ds_read_b128 v[136:139], v171 offset:128
	ds_read_b128 v[140:143], v172 offset:128
	s_waitcnt lgkmcnt(0)
	ds_write_b128 v169, v[108:111]
	ds_write_b128 v170, v[104:107]
	ds_write_b128 v169, v[100:103] offset:128
	ds_write_b128 v170, v[96:99] offset:128
	s_waitcnt vmcnt(12)
	v_pk_add_f32 v[128:129], v[128:129], v[188:189]
	v_pk_add_f32 v[130:131], v[130:131], v[190:191]
	v_pk_add_f32 v[132:133], v[132:133], v[192:193]
	v_pk_add_f32 v[134:135], v[134:135], v[194:195]
	v_pk_mul_f32 v[176:177], v[128:129], v[128:129]
	v_pk_fma_f32 v[176:177], v[130:131], v[130:131], v[176:177]
	v_pk_fma_f32 v[176:177], v[132:133], v[132:133], v[176:177]
	v_pk_fma_f32 v[176:177], v[134:135], v[134:135], v[176:177]
	v_cvt_pk_bf16_f32 v156, v128, v129
	v_cvt_pk_bf16_f32 v157, v130, v131
	v_cvt_pk_bf16_f32 v158, v132, v133
	v_cvt_pk_bf16_f32 v159, v134, v135
	global_store_dwordx4 v173, v[156:159], s[16:17]
	v_pk_add_f32 v[136:137], v[136:137], v[196:197]
	v_pk_add_f32 v[138:139], v[138:139], v[198:199]
	v_pk_add_f32 v[140:141], v[140:141], v[200:201]
	v_pk_add_f32 v[142:143], v[142:143], v[202:203]
	v_pk_fma_f32 v[176:177], v[136:137], v[136:137], v[176:177]
	v_pk_fma_f32 v[176:177], v[138:139], v[138:139], v[176:177]
	v_pk_fma_f32 v[176:177], v[140:141], v[140:141], v[176:177]
	v_pk_fma_f32 v[176:177], v[142:143], v[142:143], v[176:177]
	v_cvt_pk_bf16_f32 v160, v136, v137
	v_cvt_pk_bf16_f32 v161, v138, v139
	v_cvt_pk_bf16_f32 v162, v140, v141
	v_cvt_pk_bf16_f32 v163, v142, v143
	global_store_dwordx4 v173, v[160:163], s[16:17] offset:256
	v_add_f32_e32 v178, v176, v177
	s_nop 1
	v_add_f32_dpp v179, v178, v178 quad_perm:[1,0,3,2] row_mask:0xf bank_mask:0xf
	s_nop 1
	v_add_f32_dpp v181, v179, v179 quad_perm:[2,3,0,1] row_mask:0xf bank_mask:0xf
	s_mov_b64 exec, vcc
	global_atomic_add_f32 v174, v181, s[18:19] offset:0
	s_mov_b64 exec, s[8:9]
	global_load_dwordx4 v[188:191], v175, s[98:99]
	global_load_dwordx4 v[192:195], v175, s[98:99] offset:16
	global_load_dwordx4 v[196:199], v175, s[98:99] offset:512
	global_load_dwordx4 v[200:203], v175, s[98:99] offset:528
	s_add_u32 s98, s98, 0x10000
	s_addc_u32 s99, s99, 0
	v_add_u32_e32 v173, 0x8000, v173
	s_waitcnt lgkmcnt(0)
	ds_read_b128 v[128:131], v171
	ds_read_b128 v[132:135], v172
	ds_read_b128 v[136:139], v171 offset:128
	ds_read_b128 v[140:143], v172 offset:128
	s_waitcnt lgkmcnt(0)
	ds_write_b128 v169, v[92:95]
	ds_write_b128 v170, v[88:91]
	ds_write_b128 v169, v[84:87] offset:128
	ds_write_b128 v170, v[80:83] offset:128
	s_waitcnt vmcnt(15)
	v_pk_add_f32 v[128:129], v[128:129], v[204:205]
	v_pk_add_f32 v[130:131], v[130:131], v[206:207]
	v_pk_add_f32 v[132:133], v[132:133], v[208:209]
	v_pk_add_f32 v[134:135], v[134:135], v[210:211]
	v_pk_mul_f32 v[176:177], v[128:129], v[128:129]
	v_pk_fma_f32 v[176:177], v[130:131], v[130:131], v[176:177]
	v_pk_fma_f32 v[176:177], v[132:133], v[132:133], v[176:177]
	v_pk_fma_f32 v[176:177], v[134:135], v[134:135], v[176:177]
	v_cvt_pk_bf16_f32 v156, v128, v129
	v_cvt_pk_bf16_f32 v157, v130, v131
	v_cvt_pk_bf16_f32 v158, v132, v133
	v_cvt_pk_bf16_f32 v159, v134, v135
	global_store_dwordx4 v173, v[156:159], s[16:17]
	v_pk_add_f32 v[136:137], v[136:137], v[212:213]
	v_pk_add_f32 v[138:139], v[138:139], v[214:215]
	v_pk_add_f32 v[140:141], v[140:141], v[216:217]
	v_pk_add_f32 v[142:143], v[142:143], v[218:219]
	v_pk_fma_f32 v[176:177], v[136:137], v[136:137], v[176:177]
	v_pk_fma_f32 v[176:177], v[138:139], v[138:139], v[176:177]
	v_pk_fma_f32 v[176:177], v[140:141], v[140:141], v[176:177]
	v_pk_fma_f32 v[176:177], v[142:143], v[142:143], v[176:177]
	v_cvt_pk_bf16_f32 v160, v136, v137
	v_cvt_pk_bf16_f32 v161, v138, v139
	v_cvt_pk_bf16_f32 v162, v140, v141
	v_cvt_pk_bf16_f32 v163, v142, v143
	global_store_dwordx4 v173, v[160:163], s[16:17] offset:256
	v_add_f32_e32 v178, v176, v177
	s_nop 1
	v_add_f32_dpp v179, v178, v178 quad_perm:[1,0,3,2] row_mask:0xf bank_mask:0xf
	s_nop 1
	v_add_f32_dpp v181, v179, v179 quad_perm:[2,3,0,1] row_mask:0xf bank_mask:0xf
	s_mov_b64 exec, vcc
	global_atomic_add_f32 v174, v181, s[18:19] offset:64
	s_mov_b64 exec, s[8:9]
	global_load_dwordx4 v[204:207], v175, s[98:99]
	global_load_dwordx4 v[208:211], v175, s[98:99] offset:16
	global_load_dwordx4 v[212:215], v175, s[98:99] offset:512
	global_load_dwordx4 v[216:219], v175, s[98:99] offset:528
	s_add_u32 s98, s98, 0x10000
	s_addc_u32 s99, s99, 0
	v_add_u32_e32 v173, 0x8000, v173
	s_waitcnt lgkmcnt(0)
	ds_read_b128 v[128:131], v171
	ds_read_b128 v[132:135], v172
	ds_read_b128 v[136:139], v171 offset:128
	ds_read_b128 v[140:143], v172 offset:128
	s_waitcnt lgkmcnt(0)
	ds_write_b128 v169, v[76:79]
	ds_write_b128 v170, v[72:75]
	ds_write_b128 v169, v[68:71] offset:128
	ds_write_b128 v170, v[64:67] offset:128
	s_waitcnt vmcnt(18)
	v_pk_add_f32 v[128:129], v[128:129], v[220:221]
	v_pk_add_f32 v[130:131], v[130:131], v[222:223]
	v_pk_add_f32 v[132:133], v[132:133], v[224:225]
	v_pk_add_f32 v[134:135], v[134:135], v[226:227]
	v_pk_mul_f32 v[176:177], v[128:129], v[128:129]
	v_pk_fma_f32 v[176:177], v[130:131], v[130:131], v[176:177]
	v_pk_fma_f32 v[176:177], v[132:133], v[132:133], v[176:177]
	v_pk_fma_f32 v[176:177], v[134:135], v[134:135], v[176:177]
	v_cvt_pk_bf16_f32 v156, v128, v129
	v_cvt_pk_bf16_f32 v157, v130, v131
	v_cvt_pk_bf16_f32 v158, v132, v133
	v_cvt_pk_bf16_f32 v159, v134, v135
	global_store_dwordx4 v173, v[156:159], s[16:17]
	v_pk_add_f32 v[136:137], v[136:137], v[228:229]
	v_pk_add_f32 v[138:139], v[138:139], v[230:231]
	v_pk_add_f32 v[140:141], v[140:141], v[232:233]
	v_pk_add_f32 v[142:143], v[142:143], v[234:235]
	v_pk_fma_f32 v[176:177], v[136:137], v[136:137], v[176:177]
	v_pk_fma_f32 v[176:177], v[138:139], v[138:139], v[176:177]
	v_pk_fma_f32 v[176:177], v[140:141], v[140:141], v[176:177]
	v_pk_fma_f32 v[176:177], v[142:143], v[142:143], v[176:177]
	v_cvt_pk_bf16_f32 v160, v136, v137
	v_cvt_pk_bf16_f32 v161, v138, v139
	v_cvt_pk_bf16_f32 v162, v140, v141
	v_cvt_pk_bf16_f32 v163, v142, v143
	global_store_dwordx4 v173, v[160:163], s[16:17] offset:256
	v_add_f32_e32 v178, v176, v177
	s_nop 1
	v_add_f32_dpp v179, v178, v178 quad_perm:[1,0,3,2] row_mask:0xf bank_mask:0xf
	s_nop 1
	v_add_f32_dpp v181, v179, v179 quad_perm:[2,3,0,1] row_mask:0xf bank_mask:0xf
	s_mov_b64 exec, vcc
	global_atomic_add_f32 v174, v181, s[18:19] offset:128
	s_mov_b64 exec, s[8:9]
	global_load_dwordx4 v[220:223], v175, s[98:99]
	global_load_dwordx4 v[224:227], v175, s[98:99] offset:16
	global_load_dwordx4 v[228:231], v175, s[98:99] offset:512
	global_load_dwordx4 v[232:235], v175, s[98:99] offset:528
	s_add_u32 s98, s98, 0x10000
	s_addc_u32 s99, s99, 0
	v_add_u32_e32 v173, 0x8000, v173
	s_waitcnt lgkmcnt(0)
	ds_read_b128 v[128:131], v171
	ds_read_b128 v[132:135], v172
	ds_read_b128 v[136:139], v171 offset:128
	ds_read_b128 v[140:143], v172 offset:128
	s_waitcnt lgkmcnt(0)
	ds_write_b128 v169, v[60:63]
	ds_write_b128 v170, v[56:59]
	ds_write_b128 v169, v[52:55] offset:128
	ds_write_b128 v170, v[48:51] offset:128
	s_waitcnt vmcnt(21)
	v_pk_add_f32 v[128:129], v[128:129], v[236:237]
	v_pk_add_f32 v[130:131], v[130:131], v[238:239]
	v_pk_add_f32 v[132:133], v[132:133], v[240:241]
	v_pk_add_f32 v[134:135], v[134:135], v[242:243]
	v_pk_mul_f32 v[176:177], v[128:129], v[128:129]
	v_pk_fma_f32 v[176:177], v[130:131], v[130:131], v[176:177]
	v_pk_fma_f32 v[176:177], v[132:133], v[132:133], v[176:177]
	v_pk_fma_f32 v[176:177], v[134:135], v[134:135], v[176:177]
	v_cvt_pk_bf16_f32 v156, v128, v129
	v_cvt_pk_bf16_f32 v157, v130, v131
	v_cvt_pk_bf16_f32 v158, v132, v133
	v_cvt_pk_bf16_f32 v159, v134, v135
	global_store_dwordx4 v173, v[156:159], s[16:17]
	v_pk_add_f32 v[136:137], v[136:137], v[244:245]
	v_pk_add_f32 v[138:139], v[138:139], v[246:247]
	v_pk_add_f32 v[140:141], v[140:141], v[248:249]
	v_pk_add_f32 v[142:143], v[142:143], v[250:251]
	v_pk_fma_f32 v[176:177], v[136:137], v[136:137], v[176:177]
	v_pk_fma_f32 v[176:177], v[138:139], v[138:139], v[176:177]
	v_pk_fma_f32 v[176:177], v[140:141], v[140:141], v[176:177]
	v_pk_fma_f32 v[176:177], v[142:143], v[142:143], v[176:177]
	v_cvt_pk_bf16_f32 v160, v136, v137
	v_cvt_pk_bf16_f32 v161, v138, v139
	v_cvt_pk_bf16_f32 v162, v140, v141
	v_cvt_pk_bf16_f32 v163, v142, v143
	global_store_dwordx4 v173, v[160:163], s[16:17] offset:256
	v_add_f32_e32 v178, v176, v177
	s_nop 1
	v_add_f32_dpp v179, v178, v178 quad_perm:[1,0,3,2] row_mask:0xf bank_mask:0xf
	s_nop 1
	v_add_f32_dpp v181, v179, v179 quad_perm:[2,3,0,1] row_mask:0xf bank_mask:0xf
	s_mov_b64 exec, vcc
	global_atomic_add_f32 v174, v181, s[18:19] offset:192
	s_mov_b64 exec, s[8:9]
	global_load_dwordx4 v[236:239], v175, s[98:99]
	global_load_dwordx4 v[240:243], v175, s[98:99] offset:16
	global_load_dwordx4 v[244:247], v175, s[98:99] offset:512
	global_load_dwordx4 v[248:251], v175, s[98:99] offset:528
	v_add_u32_e32 v173, 0x28000, v173
	s_waitcnt lgkmcnt(0)
	ds_read_b128 v[128:131], v171
	ds_read_b128 v[132:135], v172
	ds_read_b128 v[136:139], v171 offset:128
	ds_read_b128 v[140:143], v172 offset:128
	s_waitcnt lgkmcnt(0)
	ds_write_b128 v169, v[44:47]
	ds_write_b128 v170, v[40:43]
	ds_write_b128 v169, v[36:39] offset:128
	ds_write_b128 v170, v[32:35] offset:128
	s_waitcnt vmcnt(21)
	v_pk_add_f32 v[128:129], v[128:129], v[188:189]
	v_pk_add_f32 v[130:131], v[130:131], v[190:191]
	v_pk_add_f32 v[132:133], v[132:133], v[192:193]
	v_pk_add_f32 v[134:135], v[134:135], v[194:195]
	v_pk_mul_f32 v[176:177], v[128:129], v[128:129]
	v_pk_fma_f32 v[176:177], v[130:131], v[130:131], v[176:177]
	v_pk_fma_f32 v[176:177], v[132:133], v[132:133], v[176:177]
	v_pk_fma_f32 v[176:177], v[134:135], v[134:135], v[176:177]
	v_cvt_pk_bf16_f32 v156, v128, v129
	v_cvt_pk_bf16_f32 v157, v130, v131
	v_cvt_pk_bf16_f32 v158, v132, v133
	v_cvt_pk_bf16_f32 v159, v134, v135
	global_store_dwordx4 v173, v[156:159], s[16:17]
	v_pk_add_f32 v[136:137], v[136:137], v[196:197]
	v_pk_add_f32 v[138:139], v[138:139], v[198:199]
	v_pk_add_f32 v[140:141], v[140:141], v[200:201]
	v_pk_add_f32 v[142:143], v[142:143], v[202:203]
	v_pk_fma_f32 v[176:177], v[136:137], v[136:137], v[176:177]
	v_pk_fma_f32 v[176:177], v[138:139], v[138:139], v[176:177]
	v_pk_fma_f32 v[176:177], v[140:141], v[140:141], v[176:177]
	v_pk_fma_f32 v[176:177], v[142:143], v[142:143], v[176:177]
	v_cvt_pk_bf16_f32 v160, v136, v137
	v_cvt_pk_bf16_f32 v161, v138, v139
	v_cvt_pk_bf16_f32 v162, v140, v141
	v_cvt_pk_bf16_f32 v163, v142, v143
	global_store_dwordx4 v173, v[160:163], s[16:17] offset:256
	v_add_f32_e32 v178, v176, v177
	s_nop 1
	v_add_f32_dpp v179, v178, v178 quad_perm:[1,0,3,2] row_mask:0xf bank_mask:0xf
	s_nop 1
	v_add_f32_dpp v181, v179, v179 quad_perm:[2,3,0,1] row_mask:0xf bank_mask:0xf
	s_mov_b64 exec, vcc
	global_atomic_add_f32 v174, v181, s[18:19] offset:512
	s_mov_b64 exec, s[8:9]
	v_add_u32_e32 v173, 0x8000, v173
	s_waitcnt lgkmcnt(0)
	ds_read_b128 v[128:131], v171
	ds_read_b128 v[132:135], v172
	ds_read_b128 v[136:139], v171 offset:128
	ds_read_b128 v[140:143], v172 offset:128
	s_waitcnt lgkmcnt(0)
	ds_write_b128 v169, v[28:31]
	ds_write_b128 v170, v[24:27]
	ds_write_b128 v169, v[20:23] offset:128
	ds_write_b128 v170, v[16:19] offset:128
	s_waitcnt vmcnt(17)
	v_pk_add_f32 v[128:129], v[128:129], v[204:205]
	v_pk_add_f32 v[130:131], v[130:131], v[206:207]
	v_pk_add_f32 v[132:133], v[132:133], v[208:209]
	v_pk_add_f32 v[134:135], v[134:135], v[210:211]
	v_pk_mul_f32 v[176:177], v[128:129], v[128:129]
	v_pk_fma_f32 v[176:177], v[130:131], v[130:131], v[176:177]
	v_pk_fma_f32 v[176:177], v[132:133], v[132:133], v[176:177]
	v_pk_fma_f32 v[176:177], v[134:135], v[134:135], v[176:177]
	v_cvt_pk_bf16_f32 v156, v128, v129
	v_cvt_pk_bf16_f32 v157, v130, v131
	v_cvt_pk_bf16_f32 v158, v132, v133
	v_cvt_pk_bf16_f32 v159, v134, v135
	global_store_dwordx4 v173, v[156:159], s[16:17]
	v_pk_add_f32 v[136:137], v[136:137], v[212:213]
	v_pk_add_f32 v[138:139], v[138:139], v[214:215]
	v_pk_add_f32 v[140:141], v[140:141], v[216:217]
	v_pk_add_f32 v[142:143], v[142:143], v[218:219]
	v_pk_fma_f32 v[176:177], v[136:137], v[136:137], v[176:177]
	v_pk_fma_f32 v[176:177], v[138:139], v[138:139], v[176:177]
	v_pk_fma_f32 v[176:177], v[140:141], v[140:141], v[176:177]
	v_pk_fma_f32 v[176:177], v[142:143], v[142:143], v[176:177]
	v_cvt_pk_bf16_f32 v160, v136, v137
	v_cvt_pk_bf16_f32 v161, v138, v139
	v_cvt_pk_bf16_f32 v162, v140, v141
	v_cvt_pk_bf16_f32 v163, v142, v143
	global_store_dwordx4 v173, v[160:163], s[16:17] offset:256
	v_add_f32_e32 v178, v176, v177
	s_nop 1
	v_add_f32_dpp v179, v178, v178 quad_perm:[1,0,3,2] row_mask:0xf bank_mask:0xf
	s_nop 1
	v_add_f32_dpp v181, v179, v179 quad_perm:[2,3,0,1] row_mask:0xf bank_mask:0xf
	s_mov_b64 exec, vcc
	global_atomic_add_f32 v174, v181, s[18:19] offset:576
	s_mov_b64 exec, s[8:9]
	v_add_u32_e32 v173, 0x8000, v173
	s_waitcnt lgkmcnt(0)
	ds_read_b128 v[128:131], v171
	ds_read_b128 v[132:135], v172
	ds_read_b128 v[136:139], v171 offset:128
	ds_read_b128 v[140:143], v172 offset:128
	s_waitcnt lgkmcnt(0)
	ds_write_b128 v169, v[12:15]
	ds_write_b128 v170, v[8:11]
	ds_write_b128 v169, v[4:7] offset:128
	ds_write_b128 v170, v[0:3] offset:128
	s_waitcnt vmcnt(13)
	v_pk_add_f32 v[128:129], v[128:129], v[220:221]
	v_pk_add_f32 v[130:131], v[130:131], v[222:223]
	v_pk_add_f32 v[132:133], v[132:133], v[224:225]
	v_pk_add_f32 v[134:135], v[134:135], v[226:227]
	v_pk_mul_f32 v[176:177], v[128:129], v[128:129]
	v_pk_fma_f32 v[176:177], v[130:131], v[130:131], v[176:177]
	v_pk_fma_f32 v[176:177], v[132:133], v[132:133], v[176:177]
	v_pk_fma_f32 v[176:177], v[134:135], v[134:135], v[176:177]
	v_cvt_pk_bf16_f32 v156, v128, v129
	v_cvt_pk_bf16_f32 v157, v130, v131
	v_cvt_pk_bf16_f32 v158, v132, v133
	v_cvt_pk_bf16_f32 v159, v134, v135
	global_store_dwordx4 v173, v[156:159], s[16:17]
	v_pk_add_f32 v[136:137], v[136:137], v[228:229]
	v_pk_add_f32 v[138:139], v[138:139], v[230:231]
	v_pk_add_f32 v[140:141], v[140:141], v[232:233]
	v_pk_add_f32 v[142:143], v[142:143], v[234:235]
	v_pk_fma_f32 v[176:177], v[136:137], v[136:137], v[176:177]
	v_pk_fma_f32 v[176:177], v[138:139], v[138:139], v[176:177]
	v_pk_fma_f32 v[176:177], v[140:141], v[140:141], v[176:177]
	v_pk_fma_f32 v[176:177], v[142:143], v[142:143], v[176:177]
	v_cvt_pk_bf16_f32 v160, v136, v137
	v_cvt_pk_bf16_f32 v161, v138, v139
	v_cvt_pk_bf16_f32 v162, v140, v141
	v_cvt_pk_bf16_f32 v163, v142, v143
	global_store_dwordx4 v173, v[160:163], s[16:17] offset:256
	v_add_f32_e32 v178, v176, v177
	s_nop 1
	v_add_f32_dpp v179, v178, v178 quad_perm:[1,0,3,2] row_mask:0xf bank_mask:0xf
	s_nop 1
	v_add_f32_dpp v181, v179, v179 quad_perm:[2,3,0,1] row_mask:0xf bank_mask:0xf
	s_mov_b64 exec, vcc
	global_atomic_add_f32 v174, v181, s[18:19] offset:640
	s_mov_b64 exec, s[8:9]
	v_add_u32_e32 v173, 0x8000, v173
	s_waitcnt lgkmcnt(0)
	ds_read_b128 v[128:131], v171
	ds_read_b128 v[132:135], v172
	ds_read_b128 v[136:139], v171 offset:128
	ds_read_b128 v[140:143], v172 offset:128
	s_waitcnt lgkmcnt(0)
	s_waitcnt vmcnt(9)
	v_pk_add_f32 v[128:129], v[128:129], v[236:237]
	v_pk_add_f32 v[130:131], v[130:131], v[238:239]
	v_pk_add_f32 v[132:133], v[132:133], v[240:241]
	v_pk_add_f32 v[134:135], v[134:135], v[242:243]
	v_pk_mul_f32 v[176:177], v[128:129], v[128:129]
	v_pk_fma_f32 v[176:177], v[130:131], v[130:131], v[176:177]
	v_pk_fma_f32 v[176:177], v[132:133], v[132:133], v[176:177]
	v_pk_fma_f32 v[176:177], v[134:135], v[134:135], v[176:177]
	v_cvt_pk_bf16_f32 v156, v128, v129
	v_cvt_pk_bf16_f32 v157, v130, v131
	v_cvt_pk_bf16_f32 v158, v132, v133
	v_cvt_pk_bf16_f32 v159, v134, v135
	global_store_dwordx4 v173, v[156:159], s[16:17]
	v_pk_add_f32 v[136:137], v[136:137], v[244:245]
	v_pk_add_f32 v[138:139], v[138:139], v[246:247]
	v_pk_add_f32 v[140:141], v[140:141], v[248:249]
	v_pk_add_f32 v[142:143], v[142:143], v[250:251]
	v_pk_fma_f32 v[176:177], v[136:137], v[136:137], v[176:177]
	v_pk_fma_f32 v[176:177], v[138:139], v[138:139], v[176:177]
	v_pk_fma_f32 v[176:177], v[140:141], v[140:141], v[176:177]
	v_pk_fma_f32 v[176:177], v[142:143], v[142:143], v[176:177]
	v_cvt_pk_bf16_f32 v160, v136, v137
	v_cvt_pk_bf16_f32 v161, v138, v139
	v_cvt_pk_bf16_f32 v162, v140, v141
	v_cvt_pk_bf16_f32 v163, v142, v143
	global_store_dwordx4 v173, v[160:163], s[16:17] offset:256
	v_add_f32_e32 v178, v176, v177
	s_nop 1
	v_add_f32_dpp v179, v178, v178 quad_perm:[1,0,3,2] row_mask:0xf bank_mask:0xf
	s_nop 1
	v_add_f32_dpp v181, v179, v179 quad_perm:[2,3,0,1] row_mask:0xf bank_mask:0xf
	s_mov_b64 exec, vcc
	global_atomic_add_f32 v174, v181, s[18:19] offset:704
	s_mov_b64 exec, s[8:9]

.LBB0_1521:
	v_and_b32_e32 v146, 63, v180
	v_and_b32_e32 v147, 15, v180
	v_bfe_u32 v148, v180, 4, 2
	v_lshrrev_b32_e32 v149, 6, v180
	v_lshlrev_b32_e32 v149, 12, v149
	v_add_u32_e32 v149, 0x20000, v149
	v_and_b32_e32 v150, 7, v147
	v_xor_b32_e32 v150, v148, v150
	v_lshlrev_b32_e32 v150, 4, v150
	v_lshl_add_u32 v150, v147, 8, v150
	v_add_u32_e32 v140, v149, v150
	v_xor_b32_e32 v141, 64, v140
	v_lshrrev_b32_e32 v151, 2, v146
	v_and_b32_e32 v152, 3, v146
	v_and_b32_e32 v153, 7, v151
	v_lshlrev_b32_e32 v154, 1, v152
	v_xor_b32_e32 v154, v154, v153
	v_lshlrev_b32_e32 v154, 4, v154
	v_lshl_add_u32 v154, v151, 8, v154
	v_add_u32_e32 v142, v149, v154
	v_xor_b32_e32 v143, 16, v142
	s_lshl_b32 s24, s55, 8
	s_add_i32 s24, s24, s44
	v_add_u32_e32 v155, s24, v151
	v_lshlrev_b32_e32 v145, 2, v155
	v_lshlrev_b32_e32 v155, 11, v155
	s_lshl_b32 s24, s54, 8
	s_add_i32 s24, s24, s45
	v_lshl_add_u32 v156, v152, 3, s24
	v_lshl_add_u32 v144, v156, 1, v155
	v_cmp_eq_u32_e32 vcc, 0, v152
	s_mov_b64 s[98:99], s[12:13]
	global_load_dwordx4 v[188:191], v144, s[98:99]
	global_load_dwordx4 v[192:195], v144, s[98:99] offset:256
	s_add_u32 s98, s98, 0x8000
	s_addc_u32 s99, s99, 0
	global_load_dwordx4 v[196:199], v144, s[98:99]
	global_load_dwordx4 v[200:203], v144, s[98:99] offset:256
	s_add_u32 s98, s98, 0x8000
	s_addc_u32 s99, s99, 0
	global_load_dwordx4 v[204:207], v144, s[98:99]
	global_load_dwordx4 v[208:211], v144, s[98:99] offset:256
	s_add_u32 s98, s98, 0x8000
	s_addc_u32 s99, s99, 0
	global_load_dwordx4 v[212:215], v144, s[98:99]
	global_load_dwordx4 v[216:219], v144, s[98:99] offset:256
	s_add_u32 s98, s98, 0x28000
	s_addc_u32 s99, s99, 0
	global_load_dwordx4 v[220:223], v144, s[98:99]
	global_load_dwordx4 v[224:227], v144, s[98:99] offset:256
	s_add_u32 s98, s98, 0x8000
	s_addc_u32 s99, s99, 0
	global_load_dwordx4 v[228:231], v144, s[98:99]
	global_load_dwordx4 v[232:235], v144, s[98:99] offset:256
	s_add_u32 s98, s98, 0x8000
	s_addc_u32 s99, s99, 0
	global_load_dwordx4 v[236:239], v144, s[98:99]
	global_load_dwordx4 v[240:243], v144, s[98:99] offset:256
	s_add_u32 s98, s98, 0x8000
	s_addc_u32 s99, s99, 0
	global_load_dwordx4 v[244:247], v144, s[98:99]
	global_load_dwordx4 v[248:251], v144, s[98:99] offset:256
	s_mov_b64 s[24:25], exec
	s_mov_b64 s[98:99], s[12:13]
	ds_write_b128 v140, v[124:127]
	ds_write_b128 v141, v[120:123]
	ds_write_b128 v140, v[116:119] offset:128
	ds_write_b128 v141, v[112:115] offset:128
	s_waitcnt lgkmcnt(0)
	ds_read_b128 v[146:149], v142
	ds_read_b128 v[150:153], v143
	ds_read_b128 v[154:157], v142 offset:128
	ds_read_b128 v[158:161], v143 offset:128
	s_waitcnt lgkmcnt(0)
	ds_write_b128 v140, v[108:111]
	ds_write_b128 v141, v[104:107]
	ds_write_b128 v140, v[100:103] offset:128
	ds_write_b128 v141, v[96:99] offset:128
	s_waitcnt vmcnt(14)
	v_lshlrev_b32_e32 v162, 16, v188
	v_and_b32_e32 v163, 0xffff0000, v188
	v_lshlrev_b32_e32 v164, 16, v189
	v_and_b32_e32 v165, 0xffff0000, v189
	v_lshlrev_b32_e32 v166, 16, v190
	v_and_b32_e32 v167, 0xffff0000, v190
	v_lshlrev_b32_e32 v168, 16, v191
	v_and_b32_e32 v169, 0xffff0000, v191
	v_pk_add_f32 v[146:147], v[146:147], v[162:163]
	v_pk_add_f32 v[148:149], v[148:149], v[164:165]
	v_pk_add_f32 v[150:151], v[150:151], v[166:167]
	v_pk_add_f32 v[152:153], v[152:153], v[168:169]
	v_pk_mul_f32 v[170:171], v[146:147], v[146:147]
	v_pk_fma_f32 v[170:171], v[148:149], v[148:149], v[170:171]
	v_pk_fma_f32 v[170:171], v[150:151], v[150:151], v[170:171]
	v_pk_fma_f32 v[170:171], v[152:153], v[152:153], v[170:171]
	v_cvt_pk_bf16_f32 v172, v146, v147
	v_cvt_pk_bf16_f32 v173, v148, v149
	v_cvt_pk_bf16_f32 v174, v150, v151
	v_cvt_pk_bf16_f32 v175, v152, v153
	global_store_dwordx4 v144, v[172:175], s[98:99]
	v_lshlrev_b32_e32 v162, 16, v192
	v_and_b32_e32 v163, 0xffff0000, v192
	v_lshlrev_b32_e32 v164, 16, v193
	v_and_b32_e32 v165, 0xffff0000, v193
	v_lshlrev_b32_e32 v166, 16, v194
	v_and_b32_e32 v167, 0xffff0000, v194
	v_lshlrev_b32_e32 v168, 16, v195
	v_and_b32_e32 v169, 0xffff0000, v195
	v_pk_add_f32 v[154:155], v[154:155], v[162:163]
	v_pk_add_f32 v[156:157], v[156:157], v[164:165]
	v_pk_add_f32 v[158:159], v[158:159], v[166:167]
	v_pk_add_f32 v[160:161], v[160:161], v[168:169]
	v_pk_fma_f32 v[170:171], v[154:155], v[154:155], v[170:171]
	v_pk_fma_f32 v[170:171], v[156:157], v[156:157], v[170:171]
	v_pk_fma_f32 v[170:171], v[158:159], v[158:159], v[170:171]
	v_pk_fma_f32 v[170:171], v[160:161], v[160:161], v[170:171]
	v_cvt_pk_bf16_f32 v176, v154, v155
	v_cvt_pk_bf16_f32 v177, v156, v157
	v_cvt_pk_bf16_f32 v178, v158, v159
	v_cvt_pk_bf16_f32 v179, v160, v161
	global_store_dwordx4 v144, v[176:179], s[98:99] offset:256
	v_add_f32_e32 v162, v170, v171
	s_nop 1
	v_add_f32_dpp v163, v162, v162 quad_perm:[1,0,3,2] row_mask:0xf bank_mask:0xf
	s_nop 1
	v_add_f32_dpp v164, v163, v163 quad_perm:[2,3,0,1] row_mask:0xf bank_mask:0xf
	s_mov_b64 exec, vcc
	global_atomic_add_f32 v145, v164, s[14:15] offset:0
	s_mov_b64 exec, s[24:25]
	s_add_u32 s98, s98, 0x8000
	s_addc_u32 s99, s99, 0
	s_waitcnt lgkmcnt(0)
	ds_read_b128 v[146:149], v142
	ds_read_b128 v[150:153], v143
	ds_read_b128 v[154:157], v142 offset:128
	ds_read_b128 v[158:161], v143 offset:128
	s_waitcnt lgkmcnt(0)
	ds_write_b128 v140, v[92:95]
	ds_write_b128 v141, v[88:91]
	ds_write_b128 v140, v[84:87] offset:128
	ds_write_b128 v141, v[80:83] offset:128
	s_waitcnt vmcnt(15)
	v_lshlrev_b32_e32 v162, 16, v196
	v_and_b32_e32 v163, 0xffff0000, v196
	v_lshlrev_b32_e32 v164, 16, v197
	v_and_b32_e32 v165, 0xffff0000, v197
	v_lshlrev_b32_e32 v166, 16, v198
	v_and_b32_e32 v167, 0xffff0000, v198
	v_lshlrev_b32_e32 v168, 16, v199
	v_and_b32_e32 v169, 0xffff0000, v199
	v_pk_add_f32 v[146:147], v[146:147], v[162:163]
	v_pk_add_f32 v[148:149], v[148:149], v[164:165]
	v_pk_add_f32 v[150:151], v[150:151], v[166:167]
	v_pk_add_f32 v[152:153], v[152:153], v[168:169]
	v_pk_mul_f32 v[170:171], v[146:147], v[146:147]
	v_pk_fma_f32 v[170:171], v[148:149], v[148:149], v[170:171]
	v_pk_fma_f32 v[170:171], v[150:151], v[150:151], v[170:171]
	v_pk_fma_f32 v[170:171], v[152:153], v[152:153], v[170:171]
	v_cvt_pk_bf16_f32 v172, v146, v147
	v_cvt_pk_bf16_f32 v173, v148, v149
	v_cvt_pk_bf16_f32 v174, v150, v151
	v_cvt_pk_bf16_f32 v175, v152, v153
	global_store_dwordx4 v144, v[172:175], s[98:99]
	v_lshlrev_b32_e32 v162, 16, v200
	v_and_b32_e32 v163, 0xffff0000, v200
	v_lshlrev_b32_e32 v164, 16, v201
	v_and_b32_e32 v165, 0xffff0000, v201
	v_lshlrev_b32_e32 v166, 16, v202
	v_and_b32_e32 v167, 0xffff0000, v202
	v_lshlrev_b32_e32 v168, 16, v203
	v_and_b32_e32 v169, 0xffff0000, v203
	v_pk_add_f32 v[154:155], v[154:155], v[162:163]
	v_pk_add_f32 v[156:157], v[156:157], v[164:165]
	v_pk_add_f32 v[158:159], v[158:159], v[166:167]
	v_pk_add_f32 v[160:161], v[160:161], v[168:169]
	v_pk_fma_f32 v[170:171], v[154:155], v[154:155], v[170:171]
	v_pk_fma_f32 v[170:171], v[156:157], v[156:157], v[170:171]
	v_pk_fma_f32 v[170:171], v[158:159], v[158:159], v[170:171]
	v_pk_fma_f32 v[170:171], v[160:161], v[160:161], v[170:171]
	v_cvt_pk_bf16_f32 v176, v154, v155
	v_cvt_pk_bf16_f32 v177, v156, v157
	v_cvt_pk_bf16_f32 v178, v158, v159
	v_cvt_pk_bf16_f32 v179, v160, v161
	global_store_dwordx4 v144, v[176:179], s[98:99] offset:256
	v_add_f32_e32 v162, v170, v171
	s_nop 1
	v_add_f32_dpp v163, v162, v162 quad_perm:[1,0,3,2] row_mask:0xf bank_mask:0xf
	s_nop 1
	v_add_f32_dpp v164, v163, v163 quad_perm:[2,3,0,1] row_mask:0xf bank_mask:0xf
	s_mov_b64 exec, vcc
	global_atomic_add_f32 v145, v164, s[14:15] offset:64
	s_mov_b64 exec, s[24:25]
	s_add_u32 s98, s98, 0x8000
	s_addc_u32 s99, s99, 0
	s_waitcnt lgkmcnt(0)
	ds_read_b128 v[146:149], v142
	ds_read_b128 v[150:153], v143
	ds_read_b128 v[154:157], v142 offset:128
	ds_read_b128 v[158:161], v143 offset:128
	s_waitcnt lgkmcnt(0)
	ds_write_b128 v140, v[76:79]
	ds_write_b128 v141, v[72:75]
	ds_write_b128 v140, v[68:71] offset:128
	ds_write_b128 v141, v[64:67] offset:128
	s_waitcnt vmcnt(16)
	v_lshlrev_b32_e32 v162, 16, v204
	v_and_b32_e32 v163, 0xffff0000, v204
	v_lshlrev_b32_e32 v164, 16, v205
	v_and_b32_e32 v165, 0xffff0000, v205
	v_lshlrev_b32_e32 v166, 16, v206
	v_and_b32_e32 v167, 0xffff0000, v206
	v_lshlrev_b32_e32 v168, 16, v207
	v_and_b32_e32 v169, 0xffff0000, v207
	v_pk_add_f32 v[146:147], v[146:147], v[162:163]
	v_pk_add_f32 v[148:149], v[148:149], v[164:165]
	v_pk_add_f32 v[150:151], v[150:151], v[166:167]
	v_pk_add_f32 v[152:153], v[152:153], v[168:169]
	v_pk_mul_f32 v[170:171], v[146:147], v[146:147]
	v_pk_fma_f32 v[170:171], v[148:149], v[148:149], v[170:171]
	v_pk_fma_f32 v[170:171], v[150:151], v[150:151], v[170:171]
	v_pk_fma_f32 v[170:171], v[152:153], v[152:153], v[170:171]
	v_cvt_pk_bf16_f32 v172, v146, v147
	v_cvt_pk_bf16_f32 v173, v148, v149
	v_cvt_pk_bf16_f32 v174, v150, v151
	v_cvt_pk_bf16_f32 v175, v152, v153
	global_store_dwordx4 v144, v[172:175], s[98:99]
	v_lshlrev_b32_e32 v162, 16, v208
	v_and_b32_e32 v163, 0xffff0000, v208
	v_lshlrev_b32_e32 v164, 16, v209
	v_and_b32_e32 v165, 0xffff0000, v209
	v_lshlrev_b32_e32 v166, 16, v210
	v_and_b32_e32 v167, 0xffff0000, v210
	v_lshlrev_b32_e32 v168, 16, v211
	v_and_b32_e32 v169, 0xffff0000, v211
	v_pk_add_f32 v[154:155], v[154:155], v[162:163]
	v_pk_add_f32 v[156:157], v[156:157], v[164:165]
	v_pk_add_f32 v[158:159], v[158:159], v[166:167]
	v_pk_add_f32 v[160:161], v[160:161], v[168:169]
	v_pk_fma_f32 v[170:171], v[154:155], v[154:155], v[170:171]
	v_pk_fma_f32 v[170:171], v[156:157], v[156:157], v[170:171]
	v_pk_fma_f32 v[170:171], v[158:159], v[158:159], v[170:171]
	v_pk_fma_f32 v[170:171], v[160:161], v[160:161], v[170:171]
	v_cvt_pk_bf16_f32 v176, v154, v155
	v_cvt_pk_bf16_f32 v177, v156, v157
	v_cvt_pk_bf16_f32 v178, v158, v159
	v_cvt_pk_bf16_f32 v179, v160, v161
	global_store_dwordx4 v144, v[176:179], s[98:99] offset:256
	v_add_f32_e32 v162, v170, v171
	s_nop 1
	v_add_f32_dpp v163, v162, v162 quad_perm:[1,0,3,2] row_mask:0xf bank_mask:0xf
	s_nop 1
	v_add_f32_dpp v164, v163, v163 quad_perm:[2,3,0,1] row_mask:0xf bank_mask:0xf
	s_mov_b64 exec, vcc
	global_atomic_add_f32 v145, v164, s[14:15] offset:128
	s_mov_b64 exec, s[24:25]
	s_add_u32 s98, s98, 0x8000
	s_addc_u32 s99, s99, 0
	s_waitcnt lgkmcnt(0)
	ds_read_b128 v[146:149], v142
	ds_read_b128 v[150:153], v143
	ds_read_b128 v[154:157], v142 offset:128
	ds_read_b128 v[158:161], v143 offset:128
	s_waitcnt lgkmcnt(0)
	ds_write_b128 v140, v[60:63]
	ds_write_b128 v141, v[56:59]
	ds_write_b128 v140, v[52:55] offset:128
	ds_write_b128 v141, v[48:51] offset:128
	s_waitcnt vmcnt(17)
	v_lshlrev_b32_e32 v162, 16, v212
	v_and_b32_e32 v163, 0xffff0000, v212
	v_lshlrev_b32_e32 v164, 16, v213
	v_and_b32_e32 v165, 0xffff0000, v213
	v_lshlrev_b32_e32 v166, 16, v214
	v_and_b32_e32 v167, 0xffff0000, v214
	v_lshlrev_b32_e32 v168, 16, v215
	v_and_b32_e32 v169, 0xffff0000, v215
	v_pk_add_f32 v[146:147], v[146:147], v[162:163]
	v_pk_add_f32 v[148:149], v[148:149], v[164:165]
	v_pk_add_f32 v[150:151], v[150:151], v[166:167]
	v_pk_add_f32 v[152:153], v[152:153], v[168:169]
	v_pk_mul_f32 v[170:171], v[146:147], v[146:147]
	v_pk_fma_f32 v[170:171], v[148:149], v[148:149], v[170:171]
	v_pk_fma_f32 v[170:171], v[150:151], v[150:151], v[170:171]
	v_pk_fma_f32 v[170:171], v[152:153], v[152:153], v[170:171]
	v_cvt_pk_bf16_f32 v172, v146, v147
	v_cvt_pk_bf16_f32 v173, v148, v149
	v_cvt_pk_bf16_f32 v174, v150, v151
	v_cvt_pk_bf16_f32 v175, v152, v153
	global_store_dwordx4 v144, v[172:175], s[98:99]
	v_lshlrev_b32_e32 v162, 16, v216
	v_and_b32_e32 v163, 0xffff0000, v216
	v_lshlrev_b32_e32 v164, 16, v217
	v_and_b32_e32 v165, 0xffff0000, v217
	v_lshlrev_b32_e32 v166, 16, v218
	v_and_b32_e32 v167, 0xffff0000, v218
	v_lshlrev_b32_e32 v168, 16, v219
	v_and_b32_e32 v169, 0xffff0000, v219
	v_pk_add_f32 v[154:155], v[154:155], v[162:163]
	v_pk_add_f32 v[156:157], v[156:157], v[164:165]
	v_pk_add_f32 v[158:159], v[158:159], v[166:167]
	v_pk_add_f32 v[160:161], v[160:161], v[168:169]
	v_pk_fma_f32 v[170:171], v[154:155], v[154:155], v[170:171]
	v_pk_fma_f32 v[170:171], v[156:157], v[156:157], v[170:171]
	v_pk_fma_f32 v[170:171], v[158:159], v[158:159], v[170:171]
	v_pk_fma_f32 v[170:171], v[160:161], v[160:161], v[170:171]
	v_cvt_pk_bf16_f32 v176, v154, v155
	v_cvt_pk_bf16_f32 v177, v156, v157
	v_cvt_pk_bf16_f32 v178, v158, v159
	v_cvt_pk_bf16_f32 v179, v160, v161
	global_store_dwordx4 v144, v[176:179], s[98:99] offset:256
	v_add_f32_e32 v162, v170, v171
	s_nop 1
	v_add_f32_dpp v163, v162, v162 quad_perm:[1,0,3,2] row_mask:0xf bank_mask:0xf
	s_nop 1
	v_add_f32_dpp v164, v163, v163 quad_perm:[2,3,0,1] row_mask:0xf bank_mask:0xf
	s_mov_b64 exec, vcc
	global_atomic_add_f32 v145, v164, s[14:15] offset:192
	s_mov_b64 exec, s[24:25]
	s_add_u32 s98, s98, 0x28000
	s_addc_u32 s99, s99, 0
	s_waitcnt lgkmcnt(0)
	ds_read_b128 v[146:149], v142
	ds_read_b128 v[150:153], v143
	ds_read_b128 v[154:157], v142 offset:128
	ds_read_b128 v[158:161], v143 offset:128
	s_waitcnt lgkmcnt(0)
	ds_write_b128 v140, v[44:47]
	ds_write_b128 v141, v[40:43]
	ds_write_b128 v140, v[36:39] offset:128
	ds_write_b128 v141, v[32:35] offset:128
	s_waitcnt vmcnt(18)
	v_lshlrev_b32_e32 v162, 16, v220
	v_and_b32_e32 v163, 0xffff0000, v220
	v_lshlrev_b32_e32 v164, 16, v221
	v_and_b32_e32 v165, 0xffff0000, v221
	v_lshlrev_b32_e32 v166, 16, v222
	v_and_b32_e32 v167, 0xffff0000, v222
	v_lshlrev_b32_e32 v168, 16, v223
	v_and_b32_e32 v169, 0xffff0000, v223
	v_pk_add_f32 v[146:147], v[146:147], v[162:163]
	v_pk_add_f32 v[148:149], v[148:149], v[164:165]
	v_pk_add_f32 v[150:151], v[150:151], v[166:167]
	v_pk_add_f32 v[152:153], v[152:153], v[168:169]
	v_pk_mul_f32 v[170:171], v[146:147], v[146:147]
	v_pk_fma_f32 v[170:171], v[148:149], v[148:149], v[170:171]
	v_pk_fma_f32 v[170:171], v[150:151], v[150:151], v[170:171]
	v_pk_fma_f32 v[170:171], v[152:153], v[152:153], v[170:171]
	v_cvt_pk_bf16_f32 v172, v146, v147
	v_cvt_pk_bf16_f32 v173, v148, v149
	v_cvt_pk_bf16_f32 v174, v150, v151
	v_cvt_pk_bf16_f32 v175, v152, v153
	global_store_dwordx4 v144, v[172:175], s[98:99]
	v_lshlrev_b32_e32 v162, 16, v224
	v_and_b32_e32 v163, 0xffff0000, v224
	v_lshlrev_b32_e32 v164, 16, v225
	v_and_b32_e32 v165, 0xffff0000, v225
	v_lshlrev_b32_e32 v166, 16, v226
	v_and_b32_e32 v167, 0xffff0000, v226
	v_lshlrev_b32_e32 v168, 16, v227
	v_and_b32_e32 v169, 0xffff0000, v227
	v_pk_add_f32 v[154:155], v[154:155], v[162:163]
	v_pk_add_f32 v[156:157], v[156:157], v[164:165]
	v_pk_add_f32 v[158:159], v[158:159], v[166:167]
	v_pk_add_f32 v[160:161], v[160:161], v[168:169]
	v_pk_fma_f32 v[170:171], v[154:155], v[154:155], v[170:171]
	v_pk_fma_f32 v[170:171], v[156:157], v[156:157], v[170:171]
	v_pk_fma_f32 v[170:171], v[158:159], v[158:159], v[170:171]
	v_pk_fma_f32 v[170:171], v[160:161], v[160:161], v[170:171]
	v_cvt_pk_bf16_f32 v176, v154, v155
	v_cvt_pk_bf16_f32 v177, v156, v157
	v_cvt_pk_bf16_f32 v178, v158, v159
	v_cvt_pk_bf16_f32 v179, v160, v161
	global_store_dwordx4 v144, v[176:179], s[98:99] offset:256
	v_add_f32_e32 v162, v170, v171
	s_nop 1
	v_add_f32_dpp v163, v162, v162 quad_perm:[1,0,3,2] row_mask:0xf bank_mask:0xf
	s_nop 1
	v_add_f32_dpp v164, v163, v163 quad_perm:[2,3,0,1] row_mask:0xf bank_mask:0xf
	s_mov_b64 exec, vcc
	global_atomic_add_f32 v145, v164, s[14:15] offset:512
	s_mov_b64 exec, s[24:25]
	s_add_u32 s98, s98, 0x8000
	s_addc_u32 s99, s99, 0
	s_waitcnt lgkmcnt(0)
	ds_read_b128 v[146:149], v142
	ds_read_b128 v[150:153], v143
	ds_read_b128 v[154:157], v142 offset:128
	ds_read_b128 v[158:161], v143 offset:128
	s_waitcnt lgkmcnt(0)
	ds_write_b128 v140, v[28:31]
	ds_write_b128 v141, v[24:27]
	ds_write_b128 v140, v[20:23] offset:128
	ds_write_b128 v141, v[16:19] offset:128
	s_waitcnt vmcnt(19)
	v_lshlrev_b32_e32 v162, 16, v228
	v_and_b32_e32 v163, 0xffff0000, v228
	v_lshlrev_b32_e32 v164, 16, v229
	v_and_b32_e32 v165, 0xffff0000, v229
	v_lshlrev_b32_e32 v166, 16, v230
	v_and_b32_e32 v167, 0xffff0000, v230
	v_lshlrev_b32_e32 v168, 16, v231
	v_and_b32_e32 v169, 0xffff0000, v231
	v_pk_add_f32 v[146:147], v[146:147], v[162:163]
	v_pk_add_f32 v[148:149], v[148:149], v[164:165]
	v_pk_add_f32 v[150:151], v[150:151], v[166:167]
	v_pk_add_f32 v[152:153], v[152:153], v[168:169]
	v_pk_mul_f32 v[170:171], v[146:147], v[146:147]
	v_pk_fma_f32 v[170:171], v[148:149], v[148:149], v[170:171]
	v_pk_fma_f32 v[170:171], v[150:151], v[150:151], v[170:171]
	v_pk_fma_f32 v[170:171], v[152:153], v[152:153], v[170:171]
	v_cvt_pk_bf16_f32 v172, v146, v147
	v_cvt_pk_bf16_f32 v173, v148, v149
	v_cvt_pk_bf16_f32 v174, v150, v151
	v_cvt_pk_bf16_f32 v175, v152, v153
	global_store_dwordx4 v144, v[172:175], s[98:99]
	v_lshlrev_b32_e32 v162, 16, v232
	v_and_b32_e32 v163, 0xffff0000, v232
	v_lshlrev_b32_e32 v164, 16, v233
	v_and_b32_e32 v165, 0xffff0000, v233
	v_lshlrev_b32_e32 v166, 16, v234
	v_and_b32_e32 v167, 0xffff0000, v234
	v_lshlrev_b32_e32 v168, 16, v235
	v_and_b32_e32 v169, 0xffff0000, v235
	v_pk_add_f32 v[154:155], v[154:155], v[162:163]
	v_pk_add_f32 v[156:157], v[156:157], v[164:165]
	v_pk_add_f32 v[158:159], v[158:159], v[166:167]
	v_pk_add_f32 v[160:161], v[160:161], v[168:169]
	v_pk_fma_f32 v[170:171], v[154:155], v[154:155], v[170:171]
	v_pk_fma_f32 v[170:171], v[156:157], v[156:157], v[170:171]
	v_pk_fma_f32 v[170:171], v[158:159], v[158:159], v[170:171]
	v_pk_fma_f32 v[170:171], v[160:161], v[160:161], v[170:171]
	v_cvt_pk_bf16_f32 v176, v154, v155
	v_cvt_pk_bf16_f32 v177, v156, v157
	v_cvt_pk_bf16_f32 v178, v158, v159
	v_cvt_pk_bf16_f32 v179, v160, v161
	global_store_dwordx4 v144, v[176:179], s[98:99] offset:256
	v_add_f32_e32 v162, v170, v171
	s_nop 1
	v_add_f32_dpp v163, v162, v162 quad_perm:[1,0,3,2] row_mask:0xf bank_mask:0xf
	s_nop 1
	v_add_f32_dpp v164, v163, v163 quad_perm:[2,3,0,1] row_mask:0xf bank_mask:0xf
	s_mov_b64 exec, vcc
	global_atomic_add_f32 v145, v164, s[14:15] offset:576
	s_mov_b64 exec, s[24:25]
	s_add_u32 s98, s98, 0x8000
	s_addc_u32 s99, s99, 0
	s_waitcnt lgkmcnt(0)
	ds_read_b128 v[146:149], v142
	ds_read_b128 v[150:153], v143
	ds_read_b128 v[154:157], v142 offset:128
	ds_read_b128 v[158:161], v143 offset:128
	s_waitcnt lgkmcnt(0)
	ds_write_b128 v140, v[12:15]
	ds_write_b128 v141, v[8:11]
	ds_write_b128 v140, v[4:7] offset:128
	ds_write_b128 v141, v[0:3] offset:128
	s_waitcnt vmcnt(20)
	v_lshlrev_b32_e32 v162, 16, v236
	v_and_b32_e32 v163, 0xffff0000, v236
	v_lshlrev_b32_e32 v164, 16, v237
	v_and_b32_e32 v165, 0xffff0000, v237
	v_lshlrev_b32_e32 v166, 16, v238
	v_and_b32_e32 v167, 0xffff0000, v238
	v_lshlrev_b32_e32 v168, 16, v239
	v_and_b32_e32 v169, 0xffff0000, v239
	v_pk_add_f32 v[146:147], v[146:147], v[162:163]
	v_pk_add_f32 v[148:149], v[148:149], v[164:165]
	v_pk_add_f32 v[150:151], v[150:151], v[166:167]
	v_pk_add_f32 v[152:153], v[152:153], v[168:169]
	v_pk_mul_f32 v[170:171], v[146:147], v[146:147]
	v_pk_fma_f32 v[170:171], v[148:149], v[148:149], v[170:171]
	v_pk_fma_f32 v[170:171], v[150:151], v[150:151], v[170:171]
	v_pk_fma_f32 v[170:171], v[152:153], v[152:153], v[170:171]
	v_cvt_pk_bf16_f32 v172, v146, v147
	v_cvt_pk_bf16_f32 v173, v148, v149
	v_cvt_pk_bf16_f32 v174, v150, v151
	v_cvt_pk_bf16_f32 v175, v152, v153
	global_store_dwordx4 v144, v[172:175], s[98:99]
	v_lshlrev_b32_e32 v162, 16, v240
	v_and_b32_e32 v163, 0xffff0000, v240
	v_lshlrev_b32_e32 v164, 16, v241
	v_and_b32_e32 v165, 0xffff0000, v241
	v_lshlrev_b32_e32 v166, 16, v242
	v_and_b32_e32 v167, 0xffff0000, v242
	v_lshlrev_b32_e32 v168, 16, v243
	v_and_b32_e32 v169, 0xffff0000, v243
	v_pk_add_f32 v[154:155], v[154:155], v[162:163]
	v_pk_add_f32 v[156:157], v[156:157], v[164:165]
	v_pk_add_f32 v[158:159], v[158:159], v[166:167]
	v_pk_add_f32 v[160:161], v[160:161], v[168:169]
	v_pk_fma_f32 v[170:171], v[154:155], v[154:155], v[170:171]
	v_pk_fma_f32 v[170:171], v[156:157], v[156:157], v[170:171]
	v_pk_fma_f32 v[170:171], v[158:159], v[158:159], v[170:171]
	v_pk_fma_f32 v[170:171], v[160:161], v[160:161], v[170:171]
	v_cvt_pk_bf16_f32 v176, v154, v155
	v_cvt_pk_bf16_f32 v177, v156, v157
	v_cvt_pk_bf16_f32 v178, v158, v159
	v_cvt_pk_bf16_f32 v179, v160, v161
	global_store_dwordx4 v144, v[176:179], s[98:99] offset:256
	v_add_f32_e32 v162, v170, v171
	s_nop 1
	v_add_f32_dpp v163, v162, v162 quad_perm:[1,0,3,2] row_mask:0xf bank_mask:0xf
	s_nop 1
	v_add_f32_dpp v164, v163, v163 quad_perm:[2,3,0,1] row_mask:0xf bank_mask:0xf
	s_mov_b64 exec, vcc
	global_atomic_add_f32 v145, v164, s[14:15] offset:640
	s_mov_b64 exec, s[24:25]
	s_add_u32 s98, s98, 0x8000
	s_addc_u32 s99, s99, 0
	s_waitcnt lgkmcnt(0)
	ds_read_b128 v[146:149], v142
	ds_read_b128 v[150:153], v143
	ds_read_b128 v[154:157], v142 offset:128
	ds_read_b128 v[158:161], v143 offset:128
	s_waitcnt lgkmcnt(0)
	s_waitcnt vmcnt(21)
	v_lshlrev_b32_e32 v162, 16, v244
	v_and_b32_e32 v163, 0xffff0000, v244
	v_lshlrev_b32_e32 v164, 16, v245
	v_and_b32_e32 v165, 0xffff0000, v245
	v_lshlrev_b32_e32 v166, 16, v246
	v_and_b32_e32 v167, 0xffff0000, v246
	v_lshlrev_b32_e32 v168, 16, v247
	v_and_b32_e32 v169, 0xffff0000, v247
	v_pk_add_f32 v[146:147], v[146:147], v[162:163]
	v_pk_add_f32 v[148:149], v[148:149], v[164:165]
	v_pk_add_f32 v[150:151], v[150:151], v[166:167]
	v_pk_add_f32 v[152:153], v[152:153], v[168:169]
	v_pk_mul_f32 v[170:171], v[146:147], v[146:147]
	v_pk_fma_f32 v[170:171], v[148:149], v[148:149], v[170:171]
	v_pk_fma_f32 v[170:171], v[150:151], v[150:151], v[170:171]
	v_pk_fma_f32 v[170:171], v[152:153], v[152:153], v[170:171]
	v_cvt_pk_bf16_f32 v172, v146, v147
	v_cvt_pk_bf16_f32 v173, v148, v149
	v_cvt_pk_bf16_f32 v174, v150, v151
	v_cvt_pk_bf16_f32 v175, v152, v153
	global_store_dwordx4 v144, v[172:175], s[98:99]
	v_lshlrev_b32_e32 v162, 16, v248
	v_and_b32_e32 v163, 0xffff0000, v248
	v_lshlrev_b32_e32 v164, 16, v249
	v_and_b32_e32 v165, 0xffff0000, v249
	v_lshlrev_b32_e32 v166, 16, v250
	v_and_b32_e32 v167, 0xffff0000, v250
	v_lshlrev_b32_e32 v168, 16, v251
	v_and_b32_e32 v169, 0xffff0000, v251
	v_pk_add_f32 v[154:155], v[154:155], v[162:163]
	v_pk_add_f32 v[156:157], v[156:157], v[164:165]
	v_pk_add_f32 v[158:159], v[158:159], v[166:167]
	v_pk_add_f32 v[160:161], v[160:161], v[168:169]
	v_pk_fma_f32 v[170:171], v[154:155], v[154:155], v[170:171]
	v_pk_fma_f32 v[170:171], v[156:157], v[156:157], v[170:171]
	v_pk_fma_f32 v[170:171], v[158:159], v[158:159], v[170:171]
	v_pk_fma_f32 v[170:171], v[160:161], v[160:161], v[170:171]
	v_cvt_pk_bf16_f32 v176, v154, v155
	v_cvt_pk_bf16_f32 v177, v156, v157
	v_cvt_pk_bf16_f32 v178, v158, v159
	v_cvt_pk_bf16_f32 v179, v160, v161
	global_store_dwordx4 v144, v[176:179], s[98:99] offset:256
	v_add_f32_e32 v162, v170, v171
	s_nop 1
	v_add_f32_dpp v163, v162, v162 quad_perm:[1,0,3,2] row_mask:0xf bank_mask:0xf
	s_nop 1
	v_add_f32_dpp v164, v163, v163 quad_perm:[2,3,0,1] row_mask:0xf bank_mask:0xf
	s_mov_b64 exec, vcc
	global_atomic_add_f32 v145, v164, s[14:15] offset:704
	s_mov_b64 exec, s[24:25]

.LBB0_1838:
	v_and_b32_e32 v146, 63, v180
	v_and_b32_e32 v147, 15, v180
	v_bfe_u32 v148, v180, 4, 2
	v_lshrrev_b32_e32 v149, 6, v180
	v_lshlrev_b32_e32 v149, 12, v149
	v_add_u32_e32 v149, 0x20000, v149
	v_and_b32_e32 v150, 7, v147
	v_xor_b32_e32 v150, v148, v150
	v_lshlrev_b32_e32 v150, 4, v150
	v_lshl_add_u32 v150, v147, 8, v150
	v_add_u32_e32 v140, v149, v150
	v_xor_b32_e32 v141, 64, v140
	v_lshrrev_b32_e32 v151, 2, v146
	v_and_b32_e32 v152, 3, v146
	v_and_b32_e32 v153, 7, v151
	v_lshlrev_b32_e32 v154, 1, v152
	v_xor_b32_e32 v154, v154, v153
	v_lshlrev_b32_e32 v154, 4, v154
	v_lshl_add_u32 v154, v151, 8, v154
	v_add_u32_e32 v142, v149, v154
	v_xor_b32_e32 v143, 16, v142
	s_lshl_b32 s21, s30, 8
	s_add_i32 s21, s21, s51
	v_add_u32_e32 v155, s21, v151
	v_lshlrev_b32_e32 v145, 2, v155
	v_lshlrev_b32_e32 v155, 11, v155
	s_lshl_b32 s21, s28, 8
	s_add_i32 s21, s21, s52
	v_lshl_add_u32 v156, v152, 3, s21
	v_lshl_add_u32 v144, v156, 1, v155
	v_cmp_eq_u32_e32 vcc, 0, v152
	s_mov_b64 s[98:99], s[10:11]
	global_load_dwordx4 v[188:191], v144, s[98:99]
	global_load_dwordx4 v[192:195], v144, s[98:99] offset:256
	s_add_u32 s98, s98, 0x8000
	s_addc_u32 s99, s99, 0
	global_load_dwordx4 v[196:199], v144, s[98:99]
	global_load_dwordx4 v[200:203], v144, s[98:99] offset:256
	s_add_u32 s98, s98, 0x8000
	s_addc_u32 s99, s99, 0
	global_load_dwordx4 v[204:207], v144, s[98:99]
	global_load_dwordx4 v[208:211], v144, s[98:99] offset:256
	s_add_u32 s98, s98, 0x8000
	s_addc_u32 s99, s99, 0
	global_load_dwordx4 v[212:215], v144, s[98:99]
	global_load_dwordx4 v[216:219], v144, s[98:99] offset:256
	s_add_u32 s98, s98, 0x28000
	s_addc_u32 s99, s99, 0
	global_load_dwordx4 v[220:223], v144, s[98:99]
	global_load_dwordx4 v[224:227], v144, s[98:99] offset:256
	s_add_u32 s98, s98, 0x8000
	s_addc_u32 s99, s99, 0
	global_load_dwordx4 v[228:231], v144, s[98:99]
	global_load_dwordx4 v[232:235], v144, s[98:99] offset:256
	s_add_u32 s98, s98, 0x8000
	s_addc_u32 s99, s99, 0
	global_load_dwordx4 v[236:239], v144, s[98:99]
	global_load_dwordx4 v[240:243], v144, s[98:99] offset:256
	s_add_u32 s98, s98, 0x8000
	s_addc_u32 s99, s99, 0
	global_load_dwordx4 v[244:247], v144, s[98:99]
	global_load_dwordx4 v[248:251], v144, s[98:99] offset:256
	s_mov_b64 s[28:29], exec
	s_mov_b64 s[98:99], s[10:11]
	ds_write_b128 v140, v[124:127]
	ds_write_b128 v141, v[120:123]
	ds_write_b128 v140, v[116:119] offset:128
	ds_write_b128 v141, v[112:115] offset:128
	s_waitcnt lgkmcnt(0)
	ds_read_b128 v[146:149], v142
	ds_read_b128 v[150:153], v143
	ds_read_b128 v[154:157], v142 offset:128
	ds_read_b128 v[158:161], v143 offset:128
	s_waitcnt lgkmcnt(0)
	ds_write_b128 v140, v[108:111]
	ds_write_b128 v141, v[104:107]
	ds_write_b128 v140, v[100:103] offset:128
	ds_write_b128 v141, v[96:99] offset:128
	s_waitcnt vmcnt(14)
	v_lshlrev_b32_e32 v162, 16, v188
	v_and_b32_e32 v163, 0xffff0000, v188
	v_lshlrev_b32_e32 v164, 16, v189
	v_and_b32_e32 v165, 0xffff0000, v189
	v_lshlrev_b32_e32 v166, 16, v190
	v_and_b32_e32 v167, 0xffff0000, v190
	v_lshlrev_b32_e32 v168, 16, v191
	v_and_b32_e32 v169, 0xffff0000, v191
	v_pk_add_f32 v[146:147], v[146:147], v[162:163]
	v_pk_add_f32 v[148:149], v[148:149], v[164:165]
	v_pk_add_f32 v[150:151], v[150:151], v[166:167]
	v_pk_add_f32 v[152:153], v[152:153], v[168:169]
	v_pk_mul_f32 v[170:171], v[146:147], v[146:147]
	v_pk_fma_f32 v[170:171], v[148:149], v[148:149], v[170:171]
	v_pk_fma_f32 v[170:171], v[150:151], v[150:151], v[170:171]
	v_pk_fma_f32 v[170:171], v[152:153], v[152:153], v[170:171]
	v_cvt_pk_bf16_f32 v172, v146, v147
	v_cvt_pk_bf16_f32 v173, v148, v149
	v_cvt_pk_bf16_f32 v174, v150, v151
	v_cvt_pk_bf16_f32 v175, v152, v153
	global_store_dwordx4 v144, v[172:175], s[98:99]
	v_lshlrev_b32_e32 v162, 16, v192
	v_and_b32_e32 v163, 0xffff0000, v192
	v_lshlrev_b32_e32 v164, 16, v193
	v_and_b32_e32 v165, 0xffff0000, v193
	v_lshlrev_b32_e32 v166, 16, v194
	v_and_b32_e32 v167, 0xffff0000, v194
	v_lshlrev_b32_e32 v168, 16, v195
	v_and_b32_e32 v169, 0xffff0000, v195
	v_pk_add_f32 v[154:155], v[154:155], v[162:163]
	v_pk_add_f32 v[156:157], v[156:157], v[164:165]
	v_pk_add_f32 v[158:159], v[158:159], v[166:167]
	v_pk_add_f32 v[160:161], v[160:161], v[168:169]
	v_pk_fma_f32 v[170:171], v[154:155], v[154:155], v[170:171]
	v_pk_fma_f32 v[170:171], v[156:157], v[156:157], v[170:171]
	v_pk_fma_f32 v[170:171], v[158:159], v[158:159], v[170:171]
	v_pk_fma_f32 v[170:171], v[160:161], v[160:161], v[170:171]
	v_cvt_pk_bf16_f32 v176, v154, v155
	v_cvt_pk_bf16_f32 v177, v156, v157
	v_cvt_pk_bf16_f32 v178, v158, v159
	v_cvt_pk_bf16_f32 v179, v160, v161
	global_store_dwordx4 v144, v[176:179], s[98:99] offset:256
	v_add_f32_e32 v162, v170, v171
	s_nop 1
	v_add_f32_dpp v163, v162, v162 quad_perm:[1,0,3,2] row_mask:0xf bank_mask:0xf
	s_nop 1
	v_add_f32_dpp v164, v163, v163 quad_perm:[2,3,0,1] row_mask:0xf bank_mask:0xf
	s_mov_b64 exec, vcc
	global_atomic_add_f32 v145, v164, s[12:13] offset:0
	s_mov_b64 exec, s[28:29]
	s_add_u32 s98, s98, 0x8000
	s_addc_u32 s99, s99, 0
	s_waitcnt lgkmcnt(0)
	ds_read_b128 v[146:149], v142
	ds_read_b128 v[150:153], v143
	ds_read_b128 v[154:157], v142 offset:128
	ds_read_b128 v[158:161], v143 offset:128
	s_waitcnt lgkmcnt(0)
	ds_write_b128 v140, v[92:95]
	ds_write_b128 v141, v[88:91]
	ds_write_b128 v140, v[84:87] offset:128
	ds_write_b128 v141, v[80:83] offset:128
	s_waitcnt vmcnt(15)
	v_lshlrev_b32_e32 v162, 16, v196
	v_and_b32_e32 v163, 0xffff0000, v196
	v_lshlrev_b32_e32 v164, 16, v197
	v_and_b32_e32 v165, 0xffff0000, v197
	v_lshlrev_b32_e32 v166, 16, v198
	v_and_b32_e32 v167, 0xffff0000, v198
	v_lshlrev_b32_e32 v168, 16, v199
	v_and_b32_e32 v169, 0xffff0000, v199
	v_pk_add_f32 v[146:147], v[146:147], v[162:163]
	v_pk_add_f32 v[148:149], v[148:149], v[164:165]
	v_pk_add_f32 v[150:151], v[150:151], v[166:167]
	v_pk_add_f32 v[152:153], v[152:153], v[168:169]
	v_pk_mul_f32 v[170:171], v[146:147], v[146:147]
	v_pk_fma_f32 v[170:171], v[148:149], v[148:149], v[170:171]
	v_pk_fma_f32 v[170:171], v[150:151], v[150:151], v[170:171]
	v_pk_fma_f32 v[170:171], v[152:153], v[152:153], v[170:171]
	v_cvt_pk_bf16_f32 v172, v146, v147
	v_cvt_pk_bf16_f32 v173, v148, v149
	v_cvt_pk_bf16_f32 v174, v150, v151
	v_cvt_pk_bf16_f32 v175, v152, v153
	global_store_dwordx4 v144, v[172:175], s[98:99]
	v_lshlrev_b32_e32 v162, 16, v200
	v_and_b32_e32 v163, 0xffff0000, v200
	v_lshlrev_b32_e32 v164, 16, v201
	v_and_b32_e32 v165, 0xffff0000, v201
	v_lshlrev_b32_e32 v166, 16, v202
	v_and_b32_e32 v167, 0xffff0000, v202
	v_lshlrev_b32_e32 v168, 16, v203
	v_and_b32_e32 v169, 0xffff0000, v203
	v_pk_add_f32 v[154:155], v[154:155], v[162:163]
	v_pk_add_f32 v[156:157], v[156:157], v[164:165]
	v_pk_add_f32 v[158:159], v[158:159], v[166:167]
	v_pk_add_f32 v[160:161], v[160:161], v[168:169]
	v_pk_fma_f32 v[170:171], v[154:155], v[154:155], v[170:171]
	v_pk_fma_f32 v[170:171], v[156:157], v[156:157], v[170:171]
	v_pk_fma_f32 v[170:171], v[158:159], v[158:159], v[170:171]
	v_pk_fma_f32 v[170:171], v[160:161], v[160:161], v[170:171]
	v_cvt_pk_bf16_f32 v176, v154, v155
	v_cvt_pk_bf16_f32 v177, v156, v157
	v_cvt_pk_bf16_f32 v178, v158, v159
	v_cvt_pk_bf16_f32 v179, v160, v161
	global_store_dwordx4 v144, v[176:179], s[98:99] offset:256
	v_add_f32_e32 v162, v170, v171
	s_nop 1
	v_add_f32_dpp v163, v162, v162 quad_perm:[1,0,3,2] row_mask:0xf bank_mask:0xf
	s_nop 1
	v_add_f32_dpp v164, v163, v163 quad_perm:[2,3,0,1] row_mask:0xf bank_mask:0xf
	s_mov_b64 exec, vcc
	global_atomic_add_f32 v145, v164, s[12:13] offset:64
	s_mov_b64 exec, s[28:29]
	s_add_u32 s98, s98, 0x8000
	s_addc_u32 s99, s99, 0
	s_waitcnt lgkmcnt(0)
	ds_read_b128 v[146:149], v142
	ds_read_b128 v[150:153], v143
	ds_read_b128 v[154:157], v142 offset:128
	ds_read_b128 v[158:161], v143 offset:128
	s_waitcnt lgkmcnt(0)
	ds_write_b128 v140, v[76:79]
	ds_write_b128 v141, v[72:75]
	ds_write_b128 v140, v[68:71] offset:128
	ds_write_b128 v141, v[64:67] offset:128
	s_waitcnt vmcnt(16)
	v_lshlrev_b32_e32 v162, 16, v204
	v_and_b32_e32 v163, 0xffff0000, v204
	v_lshlrev_b32_e32 v164, 16, v205
	v_and_b32_e32 v165, 0xffff0000, v205
	v_lshlrev_b32_e32 v166, 16, v206
	v_and_b32_e32 v167, 0xffff0000, v206
	v_lshlrev_b32_e32 v168, 16, v207
	v_and_b32_e32 v169, 0xffff0000, v207
	v_pk_add_f32 v[146:147], v[146:147], v[162:163]
	v_pk_add_f32 v[148:149], v[148:149], v[164:165]
	v_pk_add_f32 v[150:151], v[150:151], v[166:167]
	v_pk_add_f32 v[152:153], v[152:153], v[168:169]
	v_pk_mul_f32 v[170:171], v[146:147], v[146:147]
	v_pk_fma_f32 v[170:171], v[148:149], v[148:149], v[170:171]
	v_pk_fma_f32 v[170:171], v[150:151], v[150:151], v[170:171]
	v_pk_fma_f32 v[170:171], v[152:153], v[152:153], v[170:171]
	v_cvt_pk_bf16_f32 v172, v146, v147
	v_cvt_pk_bf16_f32 v173, v148, v149
	v_cvt_pk_bf16_f32 v174, v150, v151
	v_cvt_pk_bf16_f32 v175, v152, v153
	global_store_dwordx4 v144, v[172:175], s[98:99]
	v_lshlrev_b32_e32 v162, 16, v208
	v_and_b32_e32 v163, 0xffff0000, v208
	v_lshlrev_b32_e32 v164, 16, v209
	v_and_b32_e32 v165, 0xffff0000, v209
	v_lshlrev_b32_e32 v166, 16, v210
	v_and_b32_e32 v167, 0xffff0000, v210
	v_lshlrev_b32_e32 v168, 16, v211
	v_and_b32_e32 v169, 0xffff0000, v211
	v_pk_add_f32 v[154:155], v[154:155], v[162:163]
	v_pk_add_f32 v[156:157], v[156:157], v[164:165]
	v_pk_add_f32 v[158:159], v[158:159], v[166:167]
	v_pk_add_f32 v[160:161], v[160:161], v[168:169]
	v_pk_fma_f32 v[170:171], v[154:155], v[154:155], v[170:171]
	v_pk_fma_f32 v[170:171], v[156:157], v[156:157], v[170:171]
	v_pk_fma_f32 v[170:171], v[158:159], v[158:159], v[170:171]
	v_pk_fma_f32 v[170:171], v[160:161], v[160:161], v[170:171]
	v_cvt_pk_bf16_f32 v176, v154, v155
	v_cvt_pk_bf16_f32 v177, v156, v157
	v_cvt_pk_bf16_f32 v178, v158, v159
	v_cvt_pk_bf16_f32 v179, v160, v161
	global_store_dwordx4 v144, v[176:179], s[98:99] offset:256
	v_add_f32_e32 v162, v170, v171
	s_nop 1
	v_add_f32_dpp v163, v162, v162 quad_perm:[1,0,3,2] row_mask:0xf bank_mask:0xf
	s_nop 1
	v_add_f32_dpp v164, v163, v163 quad_perm:[2,3,0,1] row_mask:0xf bank_mask:0xf
	s_mov_b64 exec, vcc
	global_atomic_add_f32 v145, v164, s[12:13] offset:128
	s_mov_b64 exec, s[28:29]
	s_add_u32 s98, s98, 0x8000
	s_addc_u32 s99, s99, 0
	s_waitcnt lgkmcnt(0)
	ds_read_b128 v[146:149], v142
	ds_read_b128 v[150:153], v143
	ds_read_b128 v[154:157], v142 offset:128
	ds_read_b128 v[158:161], v143 offset:128
	s_waitcnt lgkmcnt(0)
	ds_write_b128 v140, v[60:63]
	ds_write_b128 v141, v[56:59]
	ds_write_b128 v140, v[52:55] offset:128
	ds_write_b128 v141, v[48:51] offset:128
	s_waitcnt vmcnt(17)
	v_lshlrev_b32_e32 v162, 16, v212
	v_and_b32_e32 v163, 0xffff0000, v212
	v_lshlrev_b32_e32 v164, 16, v213
	v_and_b32_e32 v165, 0xffff0000, v213
	v_lshlrev_b32_e32 v166, 16, v214
	v_and_b32_e32 v167, 0xffff0000, v214
	v_lshlrev_b32_e32 v168, 16, v215
	v_and_b32_e32 v169, 0xffff0000, v215
	v_pk_add_f32 v[146:147], v[146:147], v[162:163]
	v_pk_add_f32 v[148:149], v[148:149], v[164:165]
	v_pk_add_f32 v[150:151], v[150:151], v[166:167]
	v_pk_add_f32 v[152:153], v[152:153], v[168:169]
	v_pk_mul_f32 v[170:171], v[146:147], v[146:147]
	v_pk_fma_f32 v[170:171], v[148:149], v[148:149], v[170:171]
	v_pk_fma_f32 v[170:171], v[150:151], v[150:151], v[170:171]
	v_pk_fma_f32 v[170:171], v[152:153], v[152:153], v[170:171]
	v_cvt_pk_bf16_f32 v172, v146, v147
	v_cvt_pk_bf16_f32 v173, v148, v149
	v_cvt_pk_bf16_f32 v174, v150, v151
	v_cvt_pk_bf16_f32 v175, v152, v153
	global_store_dwordx4 v144, v[172:175], s[98:99]
	v_lshlrev_b32_e32 v162, 16, v216
	v_and_b32_e32 v163, 0xffff0000, v216
	v_lshlrev_b32_e32 v164, 16, v217
	v_and_b32_e32 v165, 0xffff0000, v217
	v_lshlrev_b32_e32 v166, 16, v218
	v_and_b32_e32 v167, 0xffff0000, v218
	v_lshlrev_b32_e32 v168, 16, v219
	v_and_b32_e32 v169, 0xffff0000, v219
	v_pk_add_f32 v[154:155], v[154:155], v[162:163]
	v_pk_add_f32 v[156:157], v[156:157], v[164:165]
	v_pk_add_f32 v[158:159], v[158:159], v[166:167]
	v_pk_add_f32 v[160:161], v[160:161], v[168:169]
	v_pk_fma_f32 v[170:171], v[154:155], v[154:155], v[170:171]
	v_pk_fma_f32 v[170:171], v[156:157], v[156:157], v[170:171]
	v_pk_fma_f32 v[170:171], v[158:159], v[158:159], v[170:171]
	v_pk_fma_f32 v[170:171], v[160:161], v[160:161], v[170:171]
	v_cvt_pk_bf16_f32 v176, v154, v155
	v_cvt_pk_bf16_f32 v177, v156, v157
	v_cvt_pk_bf16_f32 v178, v158, v159
	v_cvt_pk_bf16_f32 v179, v160, v161
	global_store_dwordx4 v144, v[176:179], s[98:99] offset:256
	v_add_f32_e32 v162, v170, v171
	s_nop 1
	v_add_f32_dpp v163, v162, v162 quad_perm:[1,0,3,2] row_mask:0xf bank_mask:0xf
	s_nop 1
	v_add_f32_dpp v164, v163, v163 quad_perm:[2,3,0,1] row_mask:0xf bank_mask:0xf
	s_mov_b64 exec, vcc
	global_atomic_add_f32 v145, v164, s[12:13] offset:192
	s_mov_b64 exec, s[28:29]
	s_add_u32 s98, s98, 0x28000
	s_addc_u32 s99, s99, 0
	s_waitcnt lgkmcnt(0)
	ds_read_b128 v[146:149], v142
	ds_read_b128 v[150:153], v143
	ds_read_b128 v[154:157], v142 offset:128
	ds_read_b128 v[158:161], v143 offset:128
	s_waitcnt lgkmcnt(0)
	ds_write_b128 v140, v[44:47]
	ds_write_b128 v141, v[40:43]
	ds_write_b128 v140, v[36:39] offset:128
	ds_write_b128 v141, v[32:35] offset:128
	s_waitcnt vmcnt(18)
	v_lshlrev_b32_e32 v162, 16, v220
	v_and_b32_e32 v163, 0xffff0000, v220
	v_lshlrev_b32_e32 v164, 16, v221
	v_and_b32_e32 v165, 0xffff0000, v221
	v_lshlrev_b32_e32 v166, 16, v222
	v_and_b32_e32 v167, 0xffff0000, v222
	v_lshlrev_b32_e32 v168, 16, v223
	v_and_b32_e32 v169, 0xffff0000, v223
	v_pk_add_f32 v[146:147], v[146:147], v[162:163]
	v_pk_add_f32 v[148:149], v[148:149], v[164:165]
	v_pk_add_f32 v[150:151], v[150:151], v[166:167]
	v_pk_add_f32 v[152:153], v[152:153], v[168:169]
	v_pk_mul_f32 v[170:171], v[146:147], v[146:147]
	v_pk_fma_f32 v[170:171], v[148:149], v[148:149], v[170:171]
	v_pk_fma_f32 v[170:171], v[150:151], v[150:151], v[170:171]
	v_pk_fma_f32 v[170:171], v[152:153], v[152:153], v[170:171]
	v_cvt_pk_bf16_f32 v172, v146, v147
	v_cvt_pk_bf16_f32 v173, v148, v149
	v_cvt_pk_bf16_f32 v174, v150, v151
	v_cvt_pk_bf16_f32 v175, v152, v153
	global_store_dwordx4 v144, v[172:175], s[98:99]
	v_lshlrev_b32_e32 v162, 16, v224
	v_and_b32_e32 v163, 0xffff0000, v224
	v_lshlrev_b32_e32 v164, 16, v225
	v_and_b32_e32 v165, 0xffff0000, v225
	v_lshlrev_b32_e32 v166, 16, v226
	v_and_b32_e32 v167, 0xffff0000, v226
	v_lshlrev_b32_e32 v168, 16, v227
	v_and_b32_e32 v169, 0xffff0000, v227
	v_pk_add_f32 v[154:155], v[154:155], v[162:163]
	v_pk_add_f32 v[156:157], v[156:157], v[164:165]
	v_pk_add_f32 v[158:159], v[158:159], v[166:167]
	v_pk_add_f32 v[160:161], v[160:161], v[168:169]
	v_pk_fma_f32 v[170:171], v[154:155], v[154:155], v[170:171]
	v_pk_fma_f32 v[170:171], v[156:157], v[156:157], v[170:171]
	v_pk_fma_f32 v[170:171], v[158:159], v[158:159], v[170:171]
	v_pk_fma_f32 v[170:171], v[160:161], v[160:161], v[170:171]
	v_cvt_pk_bf16_f32 v176, v154, v155
	v_cvt_pk_bf16_f32 v177, v156, v157
	v_cvt_pk_bf16_f32 v178, v158, v159
	v_cvt_pk_bf16_f32 v179, v160, v161
	global_store_dwordx4 v144, v[176:179], s[98:99] offset:256
	v_add_f32_e32 v162, v170, v171
	s_nop 1
	v_add_f32_dpp v163, v162, v162 quad_perm:[1,0,3,2] row_mask:0xf bank_mask:0xf
	s_nop 1
	v_add_f32_dpp v164, v163, v163 quad_perm:[2,3,0,1] row_mask:0xf bank_mask:0xf
	s_mov_b64 exec, vcc
	global_atomic_add_f32 v145, v164, s[12:13] offset:512
	s_mov_b64 exec, s[28:29]
	s_add_u32 s98, s98, 0x8000
	s_addc_u32 s99, s99, 0
	s_waitcnt lgkmcnt(0)
	ds_read_b128 v[146:149], v142
	ds_read_b128 v[150:153], v143
	ds_read_b128 v[154:157], v142 offset:128
	ds_read_b128 v[158:161], v143 offset:128
	s_waitcnt lgkmcnt(0)
	ds_write_b128 v140, v[28:31]
	ds_write_b128 v141, v[24:27]
	ds_write_b128 v140, v[20:23] offset:128
	ds_write_b128 v141, v[16:19] offset:128
	s_waitcnt vmcnt(19)
	v_lshlrev_b32_e32 v162, 16, v228
	v_and_b32_e32 v163, 0xffff0000, v228
	v_lshlrev_b32_e32 v164, 16, v229
	v_and_b32_e32 v165, 0xffff0000, v229
	v_lshlrev_b32_e32 v166, 16, v230
	v_and_b32_e32 v167, 0xffff0000, v230
	v_lshlrev_b32_e32 v168, 16, v231
	v_and_b32_e32 v169, 0xffff0000, v231
	v_pk_add_f32 v[146:147], v[146:147], v[162:163]
	v_pk_add_f32 v[148:149], v[148:149], v[164:165]
	v_pk_add_f32 v[150:151], v[150:151], v[166:167]
	v_pk_add_f32 v[152:153], v[152:153], v[168:169]
	v_pk_mul_f32 v[170:171], v[146:147], v[146:147]
	v_pk_fma_f32 v[170:171], v[148:149], v[148:149], v[170:171]
	v_pk_fma_f32 v[170:171], v[150:151], v[150:151], v[170:171]
	v_pk_fma_f32 v[170:171], v[152:153], v[152:153], v[170:171]
	v_cvt_pk_bf16_f32 v172, v146, v147
	v_cvt_pk_bf16_f32 v173, v148, v149
	v_cvt_pk_bf16_f32 v174, v150, v151
	v_cvt_pk_bf16_f32 v175, v152, v153
	global_store_dwordx4 v144, v[172:175], s[98:99]
	v_lshlrev_b32_e32 v162, 16, v232
	v_and_b32_e32 v163, 0xffff0000, v232
	v_lshlrev_b32_e32 v164, 16, v233
	v_and_b32_e32 v165, 0xffff0000, v233
	v_lshlrev_b32_e32 v166, 16, v234
	v_and_b32_e32 v167, 0xffff0000, v234
	v_lshlrev_b32_e32 v168, 16, v235
	v_and_b32_e32 v169, 0xffff0000, v235
	v_pk_add_f32 v[154:155], v[154:155], v[162:163]
	v_pk_add_f32 v[156:157], v[156:157], v[164:165]
	v_pk_add_f32 v[158:159], v[158:159], v[166:167]
	v_pk_add_f32 v[160:161], v[160:161], v[168:169]
	v_pk_fma_f32 v[170:171], v[154:155], v[154:155], v[170:171]
	v_pk_fma_f32 v[170:171], v[156:157], v[156:157], v[170:171]
	v_pk_fma_f32 v[170:171], v[158:159], v[158:159], v[170:171]
	v_pk_fma_f32 v[170:171], v[160:161], v[160:161], v[170:171]
	v_cvt_pk_bf16_f32 v176, v154, v155
	v_cvt_pk_bf16_f32 v177, v156, v157
	v_cvt_pk_bf16_f32 v178, v158, v159
	v_cvt_pk_bf16_f32 v179, v160, v161
	global_store_dwordx4 v144, v[176:179], s[98:99] offset:256
	v_add_f32_e32 v162, v170, v171
	s_nop 1
	v_add_f32_dpp v163, v162, v162 quad_perm:[1,0,3,2] row_mask:0xf bank_mask:0xf
	s_nop 1
	v_add_f32_dpp v164, v163, v163 quad_perm:[2,3,0,1] row_mask:0xf bank_mask:0xf
	s_mov_b64 exec, vcc
	global_atomic_add_f32 v145, v164, s[12:13] offset:576
	s_mov_b64 exec, s[28:29]
	s_add_u32 s98, s98, 0x8000
	s_addc_u32 s99, s99, 0
	s_waitcnt lgkmcnt(0)
	ds_read_b128 v[146:149], v142
	ds_read_b128 v[150:153], v143
	ds_read_b128 v[154:157], v142 offset:128
	ds_read_b128 v[158:161], v143 offset:128
	s_waitcnt lgkmcnt(0)
	ds_write_b128 v140, v[12:15]
	ds_write_b128 v141, v[8:11]
	ds_write_b128 v140, v[4:7] offset:128
	ds_write_b128 v141, v[0:3] offset:128
	s_waitcnt vmcnt(20)
	v_lshlrev_b32_e32 v162, 16, v236
	v_and_b32_e32 v163, 0xffff0000, v236
	v_lshlrev_b32_e32 v164, 16, v237
	v_and_b32_e32 v165, 0xffff0000, v237
	v_lshlrev_b32_e32 v166, 16, v238
	v_and_b32_e32 v167, 0xffff0000, v238
	v_lshlrev_b32_e32 v168, 16, v239
	v_and_b32_e32 v169, 0xffff0000, v239
	v_pk_add_f32 v[146:147], v[146:147], v[162:163]
	v_pk_add_f32 v[148:149], v[148:149], v[164:165]
	v_pk_add_f32 v[150:151], v[150:151], v[166:167]
	v_pk_add_f32 v[152:153], v[152:153], v[168:169]
	v_pk_mul_f32 v[170:171], v[146:147], v[146:147]
	v_pk_fma_f32 v[170:171], v[148:149], v[148:149], v[170:171]
	v_pk_fma_f32 v[170:171], v[150:151], v[150:151], v[170:171]
	v_pk_fma_f32 v[170:171], v[152:153], v[152:153], v[170:171]
	v_cvt_pk_bf16_f32 v172, v146, v147
	v_cvt_pk_bf16_f32 v173, v148, v149
	v_cvt_pk_bf16_f32 v174, v150, v151
	v_cvt_pk_bf16_f32 v175, v152, v153
	global_store_dwordx4 v144, v[172:175], s[98:99]
	v_lshlrev_b32_e32 v162, 16, v240
	v_and_b32_e32 v163, 0xffff0000, v240
	v_lshlrev_b32_e32 v164, 16, v241
	v_and_b32_e32 v165, 0xffff0000, v241
	v_lshlrev_b32_e32 v166, 16, v242
	v_and_b32_e32 v167, 0xffff0000, v242
	v_lshlrev_b32_e32 v168, 16, v243
	v_and_b32_e32 v169, 0xffff0000, v243
	v_pk_add_f32 v[154:155], v[154:155], v[162:163]
	v_pk_add_f32 v[156:157], v[156:157], v[164:165]
	v_pk_add_f32 v[158:159], v[158:159], v[166:167]
	v_pk_add_f32 v[160:161], v[160:161], v[168:169]
	v_pk_fma_f32 v[170:171], v[154:155], v[154:155], v[170:171]
	v_pk_fma_f32 v[170:171], v[156:157], v[156:157], v[170:171]
	v_pk_fma_f32 v[170:171], v[158:159], v[158:159], v[170:171]
	v_pk_fma_f32 v[170:171], v[160:161], v[160:161], v[170:171]
	v_cvt_pk_bf16_f32 v176, v154, v155
	v_cvt_pk_bf16_f32 v177, v156, v157
	v_cvt_pk_bf16_f32 v178, v158, v159
	v_cvt_pk_bf16_f32 v179, v160, v161
	global_store_dwordx4 v144, v[176:179], s[98:99] offset:256
	v_add_f32_e32 v162, v170, v171
	s_nop 1
	v_add_f32_dpp v163, v162, v162 quad_perm:[1,0,3,2] row_mask:0xf bank_mask:0xf
	s_nop 1
	v_add_f32_dpp v164, v163, v163 quad_perm:[2,3,0,1] row_mask:0xf bank_mask:0xf
	s_mov_b64 exec, vcc
	global_atomic_add_f32 v145, v164, s[12:13] offset:640
	s_mov_b64 exec, s[28:29]
	s_add_u32 s98, s98, 0x8000
	s_addc_u32 s99, s99, 0
	s_waitcnt lgkmcnt(0)
	ds_read_b128 v[146:149], v142
	ds_read_b128 v[150:153], v143
	ds_read_b128 v[154:157], v142 offset:128
	ds_read_b128 v[158:161], v143 offset:128
	s_waitcnt lgkmcnt(0)
	s_waitcnt vmcnt(21)
	v_lshlrev_b32_e32 v162, 16, v244
	v_and_b32_e32 v163, 0xffff0000, v244
	v_lshlrev_b32_e32 v164, 16, v245
	v_and_b32_e32 v165, 0xffff0000, v245
	v_lshlrev_b32_e32 v166, 16, v246
	v_and_b32_e32 v167, 0xffff0000, v246
	v_lshlrev_b32_e32 v168, 16, v247
	v_and_b32_e32 v169, 0xffff0000, v247
	v_pk_add_f32 v[146:147], v[146:147], v[162:163]
	v_pk_add_f32 v[148:149], v[148:149], v[164:165]
	v_pk_add_f32 v[150:151], v[150:151], v[166:167]
	v_pk_add_f32 v[152:153], v[152:153], v[168:169]
	v_pk_mul_f32 v[170:171], v[146:147], v[146:147]
	v_pk_fma_f32 v[170:171], v[148:149], v[148:149], v[170:171]
	v_pk_fma_f32 v[170:171], v[150:151], v[150:151], v[170:171]
	v_pk_fma_f32 v[170:171], v[152:153], v[152:153], v[170:171]
	v_cvt_pk_bf16_f32 v172, v146, v147
	v_cvt_pk_bf16_f32 v173, v148, v149
	v_cvt_pk_bf16_f32 v174, v150, v151
	v_cvt_pk_bf16_f32 v175, v152, v153
	global_store_dwordx4 v144, v[172:175], s[98:99]
	v_lshlrev_b32_e32 v162, 16, v248
	v_and_b32_e32 v163, 0xffff0000, v248
	v_lshlrev_b32_e32 v164, 16, v249
	v_and_b32_e32 v165, 0xffff0000, v249
	v_lshlrev_b32_e32 v166, 16, v250
	v_and_b32_e32 v167, 0xffff0000, v250
	v_lshlrev_b32_e32 v168, 16, v251
	v_and_b32_e32 v169, 0xffff0000, v251
	v_pk_add_f32 v[154:155], v[154:155], v[162:163]
	v_pk_add_f32 v[156:157], v[156:157], v[164:165]
	v_pk_add_f32 v[158:159], v[158:159], v[166:167]
	v_pk_add_f32 v[160:161], v[160:161], v[168:169]
	v_pk_fma_f32 v[170:171], v[154:155], v[154:155], v[170:171]
	v_pk_fma_f32 v[170:171], v[156:157], v[156:157], v[170:171]
	v_pk_fma_f32 v[170:171], v[158:159], v[158:159], v[170:171]
	v_pk_fma_f32 v[170:171], v[160:161], v[160:161], v[170:171]
	v_cvt_pk_bf16_f32 v176, v154, v155
	v_cvt_pk_bf16_f32 v177, v156, v157
	v_cvt_pk_bf16_f32 v178, v158, v159
	v_cvt_pk_bf16_f32 v179, v160, v161
	global_store_dwordx4 v144, v[176:179], s[98:99] offset:256
	v_add_f32_e32 v162, v170, v171
	s_nop 1
	v_add_f32_dpp v163, v162, v162 quad_perm:[1,0,3,2] row_mask:0xf bank_mask:0xf
	s_nop 1
	v_add_f32_dpp v164, v163, v163 quad_perm:[2,3,0,1] row_mask:0xf bank_mask:0xf
	s_mov_b64 exec, vcc
	global_atomic_add_f32 v145, v164, s[12:13] offset:704
	s_mov_b64 exec, s[28:29]

.LBB0_1920:
	v_and_b32_e32 v146, 63, v180
	v_and_b32_e32 v147, 15, v180
	v_bfe_u32 v148, v180, 4, 2
	v_lshrrev_b32_e32 v149, 6, v180
	v_lshlrev_b32_e32 v149, 12, v149
	v_add_u32_e32 v149, 0x20000, v149
	v_and_b32_e32 v150, 7, v147
	v_xor_b32_e32 v150, v148, v150
	v_lshlrev_b32_e32 v150, 4, v150
	v_lshl_add_u32 v150, v147, 8, v150
	v_add_u32_e32 v140, v149, v150
	v_xor_b32_e32 v141, 64, v140
	v_lshrrev_b32_e32 v151, 2, v146
	v_and_b32_e32 v152, 3, v146
	v_and_b32_e32 v153, 7, v151
	v_lshlrev_b32_e32 v154, 1, v152
	v_xor_b32_e32 v154, v154, v153
	v_lshlrev_b32_e32 v154, 4, v154
	v_lshl_add_u32 v154, v151, 8, v154
	v_add_u32_e32 v142, v149, v154
	v_xor_b32_e32 v143, 16, v142
	s_lshl_b32 s18, s48, 8
	s_add_i32 s18, s18, s37
	v_add_u32_e32 v155, s18, v151
	v_lshlrev_b32_e32 v145, 2, v155
	v_lshlrev_b32_e32 v155, 11, v155
	s_lshl_b32 s18, s45, 8
	s_add_i32 s18, s18, s38
	v_lshl_add_u32 v156, v152, 3, s18
	v_lshl_add_u32 v144, v156, 1, v155
	v_cmp_eq_u32_e32 vcc, 0, v152
	s_mov_b64 s[98:99], s[8:9]
	global_load_dwordx4 v[188:191], v144, s[98:99]
	global_load_dwordx4 v[192:195], v144, s[98:99] offset:256
	s_add_u32 s98, s98, 0x8000
	s_addc_u32 s99, s99, 0
	global_load_dwordx4 v[196:199], v144, s[98:99]
	global_load_dwordx4 v[200:203], v144, s[98:99] offset:256
	s_add_u32 s98, s98, 0x8000
	s_addc_u32 s99, s99, 0
	global_load_dwordx4 v[204:207], v144, s[98:99]
	global_load_dwordx4 v[208:211], v144, s[98:99] offset:256
	s_add_u32 s98, s98, 0x8000
	s_addc_u32 s99, s99, 0
	global_load_dwordx4 v[212:215], v144, s[98:99]
	global_load_dwordx4 v[216:219], v144, s[98:99] offset:256
	s_add_u32 s98, s98, 0x28000
	s_addc_u32 s99, s99, 0
	global_load_dwordx4 v[220:223], v144, s[98:99]
	global_load_dwordx4 v[224:227], v144, s[98:99] offset:256
	s_add_u32 s98, s98, 0x8000
	s_addc_u32 s99, s99, 0
	global_load_dwordx4 v[228:231], v144, s[98:99]
	global_load_dwordx4 v[232:235], v144, s[98:99] offset:256
	s_add_u32 s98, s98, 0x8000
	s_addc_u32 s99, s99, 0
	global_load_dwordx4 v[236:239], v144, s[98:99]
	global_load_dwordx4 v[240:243], v144, s[98:99] offset:256
	s_add_u32 s98, s98, 0x8000
	s_addc_u32 s99, s99, 0
	global_load_dwordx4 v[244:247], v144, s[98:99]
	global_load_dwordx4 v[248:251], v144, s[98:99] offset:256
	s_mov_b64 s[18:19], exec
	s_mov_b64 s[98:99], s[8:9]
	ds_write_b128 v140, v[124:127]
	ds_write_b128 v141, v[120:123]
	ds_write_b128 v140, v[116:119] offset:128
	ds_write_b128 v141, v[112:115] offset:128
	s_waitcnt lgkmcnt(0)
	ds_read_b128 v[146:149], v142
	ds_read_b128 v[150:153], v143
	ds_read_b128 v[154:157], v142 offset:128
	ds_read_b128 v[158:161], v143 offset:128
	s_waitcnt lgkmcnt(0)
	ds_write_b128 v140, v[108:111]
	ds_write_b128 v141, v[104:107]
	ds_write_b128 v140, v[100:103] offset:128
	ds_write_b128 v141, v[96:99] offset:128
	s_waitcnt vmcnt(14)
	v_lshlrev_b32_e32 v162, 16, v188
	v_and_b32_e32 v163, 0xffff0000, v188
	v_lshlrev_b32_e32 v164, 16, v189
	v_and_b32_e32 v165, 0xffff0000, v189
	v_lshlrev_b32_e32 v166, 16, v190
	v_and_b32_e32 v167, 0xffff0000, v190
	v_lshlrev_b32_e32 v168, 16, v191
	v_and_b32_e32 v169, 0xffff0000, v191
	v_pk_add_f32 v[146:147], v[146:147], v[162:163]
	v_pk_add_f32 v[148:149], v[148:149], v[164:165]
	v_pk_add_f32 v[150:151], v[150:151], v[166:167]
	v_pk_add_f32 v[152:153], v[152:153], v[168:169]
	v_pk_mul_f32 v[170:171], v[146:147], v[146:147]
	v_pk_fma_f32 v[170:171], v[148:149], v[148:149], v[170:171]
	v_pk_fma_f32 v[170:171], v[150:151], v[150:151], v[170:171]
	v_pk_fma_f32 v[170:171], v[152:153], v[152:153], v[170:171]
	v_cvt_pk_bf16_f32 v172, v146, v147
	v_cvt_pk_bf16_f32 v173, v148, v149
	v_cvt_pk_bf16_f32 v174, v150, v151
	v_cvt_pk_bf16_f32 v175, v152, v153
	global_store_dwordx4 v144, v[172:175], s[98:99]
	v_lshlrev_b32_e32 v162, 16, v192
	v_and_b32_e32 v163, 0xffff0000, v192
	v_lshlrev_b32_e32 v164, 16, v193
	v_and_b32_e32 v165, 0xffff0000, v193
	v_lshlrev_b32_e32 v166, 16, v194
	v_and_b32_e32 v167, 0xffff0000, v194
	v_lshlrev_b32_e32 v168, 16, v195
	v_and_b32_e32 v169, 0xffff0000, v195
	v_pk_add_f32 v[154:155], v[154:155], v[162:163]
	v_pk_add_f32 v[156:157], v[156:157], v[164:165]
	v_pk_add_f32 v[158:159], v[158:159], v[166:167]
	v_pk_add_f32 v[160:161], v[160:161], v[168:169]
	v_pk_fma_f32 v[170:171], v[154:155], v[154:155], v[170:171]
	v_pk_fma_f32 v[170:171], v[156:157], v[156:157], v[170:171]
	v_pk_fma_f32 v[170:171], v[158:159], v[158:159], v[170:171]
	v_pk_fma_f32 v[170:171], v[160:161], v[160:161], v[170:171]
	v_cvt_pk_bf16_f32 v176, v154, v155
	v_cvt_pk_bf16_f32 v177, v156, v157
	v_cvt_pk_bf16_f32 v178, v158, v159
	v_cvt_pk_bf16_f32 v179, v160, v161
	global_store_dwordx4 v144, v[176:179], s[98:99] offset:256
	v_add_f32_e32 v162, v170, v171
	s_nop 1
	v_add_f32_dpp v163, v162, v162 quad_perm:[1,0,3,2] row_mask:0xf bank_mask:0xf
	s_nop 1
	v_add_f32_dpp v164, v163, v163 quad_perm:[2,3,0,1] row_mask:0xf bank_mask:0xf
	s_mov_b64 exec, vcc
	global_atomic_add_f32 v145, v164, s[10:11] offset:0
	s_mov_b64 exec, s[18:19]
	s_add_u32 s98, s98, 0x8000
	s_addc_u32 s99, s99, 0
	s_waitcnt lgkmcnt(0)
	ds_read_b128 v[146:149], v142
	ds_read_b128 v[150:153], v143
	ds_read_b128 v[154:157], v142 offset:128
	ds_read_b128 v[158:161], v143 offset:128
	s_waitcnt lgkmcnt(0)
	ds_write_b128 v140, v[92:95]
	ds_write_b128 v141, v[88:91]
	ds_write_b128 v140, v[84:87] offset:128
	ds_write_b128 v141, v[80:83] offset:128
	s_waitcnt vmcnt(15)
	v_lshlrev_b32_e32 v162, 16, v196
	v_and_b32_e32 v163, 0xffff0000, v196
	v_lshlrev_b32_e32 v164, 16, v197
	v_and_b32_e32 v165, 0xffff0000, v197
	v_lshlrev_b32_e32 v166, 16, v198
	v_and_b32_e32 v167, 0xffff0000, v198
	v_lshlrev_b32_e32 v168, 16, v199
	v_and_b32_e32 v169, 0xffff0000, v199
	v_pk_add_f32 v[146:147], v[146:147], v[162:163]
	v_pk_add_f32 v[148:149], v[148:149], v[164:165]
	v_pk_add_f32 v[150:151], v[150:151], v[166:167]
	v_pk_add_f32 v[152:153], v[152:153], v[168:169]
	v_pk_mul_f32 v[170:171], v[146:147], v[146:147]
	v_pk_fma_f32 v[170:171], v[148:149], v[148:149], v[170:171]
	v_pk_fma_f32 v[170:171], v[150:151], v[150:151], v[170:171]
	v_pk_fma_f32 v[170:171], v[152:153], v[152:153], v[170:171]
	v_cvt_pk_bf16_f32 v172, v146, v147
	v_cvt_pk_bf16_f32 v173, v148, v149
	v_cvt_pk_bf16_f32 v174, v150, v151
	v_cvt_pk_bf16_f32 v175, v152, v153
	global_store_dwordx4 v144, v[172:175], s[98:99]
	v_lshlrev_b32_e32 v162, 16, v200
	v_and_b32_e32 v163, 0xffff0000, v200
	v_lshlrev_b32_e32 v164, 16, v201
	v_and_b32_e32 v165, 0xffff0000, v201
	v_lshlrev_b32_e32 v166, 16, v202
	v_and_b32_e32 v167, 0xffff0000, v202
	v_lshlrev_b32_e32 v168, 16, v203
	v_and_b32_e32 v169, 0xffff0000, v203
	v_pk_add_f32 v[154:155], v[154:155], v[162:163]
	v_pk_add_f32 v[156:157], v[156:157], v[164:165]
	v_pk_add_f32 v[158:159], v[158:159], v[166:167]
	v_pk_add_f32 v[160:161], v[160:161], v[168:169]
	v_pk_fma_f32 v[170:171], v[154:155], v[154:155], v[170:171]
	v_pk_fma_f32 v[170:171], v[156:157], v[156:157], v[170:171]
	v_pk_fma_f32 v[170:171], v[158:159], v[158:159], v[170:171]
	v_pk_fma_f32 v[170:171], v[160:161], v[160:161], v[170:171]
	v_cvt_pk_bf16_f32 v176, v154, v155
	v_cvt_pk_bf16_f32 v177, v156, v157
	v_cvt_pk_bf16_f32 v178, v158, v159
	v_cvt_pk_bf16_f32 v179, v160, v161
	global_store_dwordx4 v144, v[176:179], s[98:99] offset:256
	v_add_f32_e32 v162, v170, v171
	s_nop 1
	v_add_f32_dpp v163, v162, v162 quad_perm:[1,0,3,2] row_mask:0xf bank_mask:0xf
	s_nop 1
	v_add_f32_dpp v164, v163, v163 quad_perm:[2,3,0,1] row_mask:0xf bank_mask:0xf
	s_mov_b64 exec, vcc
	global_atomic_add_f32 v145, v164, s[10:11] offset:64
	s_mov_b64 exec, s[18:19]
	s_add_u32 s98, s98, 0x8000
	s_addc_u32 s99, s99, 0
	s_waitcnt lgkmcnt(0)
	ds_read_b128 v[146:149], v142
	ds_read_b128 v[150:153], v143
	ds_read_b128 v[154:157], v142 offset:128
	ds_read_b128 v[158:161], v143 offset:128
	s_waitcnt lgkmcnt(0)
	ds_write_b128 v140, v[76:79]
	ds_write_b128 v141, v[72:75]
	ds_write_b128 v140, v[68:71] offset:128
	ds_write_b128 v141, v[64:67] offset:128
	s_waitcnt vmcnt(16)
	v_lshlrev_b32_e32 v162, 16, v204
	v_and_b32_e32 v163, 0xffff0000, v204
	v_lshlrev_b32_e32 v164, 16, v205
	v_and_b32_e32 v165, 0xffff0000, v205
	v_lshlrev_b32_e32 v166, 16, v206
	v_and_b32_e32 v167, 0xffff0000, v206
	v_lshlrev_b32_e32 v168, 16, v207
	v_and_b32_e32 v169, 0xffff0000, v207
	v_pk_add_f32 v[146:147], v[146:147], v[162:163]
	v_pk_add_f32 v[148:149], v[148:149], v[164:165]
	v_pk_add_f32 v[150:151], v[150:151], v[166:167]
	v_pk_add_f32 v[152:153], v[152:153], v[168:169]
	v_pk_mul_f32 v[170:171], v[146:147], v[146:147]
	v_pk_fma_f32 v[170:171], v[148:149], v[148:149], v[170:171]
	v_pk_fma_f32 v[170:171], v[150:151], v[150:151], v[170:171]
	v_pk_fma_f32 v[170:171], v[152:153], v[152:153], v[170:171]
	v_cvt_pk_bf16_f32 v172, v146, v147
	v_cvt_pk_bf16_f32 v173, v148, v149
	v_cvt_pk_bf16_f32 v174, v150, v151
	v_cvt_pk_bf16_f32 v175, v152, v153
	global_store_dwordx4 v144, v[172:175], s[98:99]
	v_lshlrev_b32_e32 v162, 16, v208
	v_and_b32_e32 v163, 0xffff0000, v208
	v_lshlrev_b32_e32 v164, 16, v209
	v_and_b32_e32 v165, 0xffff0000, v209
	v_lshlrev_b32_e32 v166, 16, v210
	v_and_b32_e32 v167, 0xffff0000, v210
	v_lshlrev_b32_e32 v168, 16, v211
	v_and_b32_e32 v169, 0xffff0000, v211
	v_pk_add_f32 v[154:155], v[154:155], v[162:163]
	v_pk_add_f32 v[156:157], v[156:157], v[164:165]
	v_pk_add_f32 v[158:159], v[158:159], v[166:167]
	v_pk_add_f32 v[160:161], v[160:161], v[168:169]
	v_pk_fma_f32 v[170:171], v[154:155], v[154:155], v[170:171]
	v_pk_fma_f32 v[170:171], v[156:157], v[156:157], v[170:171]
	v_pk_fma_f32 v[170:171], v[158:159], v[158:159], v[170:171]
	v_pk_fma_f32 v[170:171], v[160:161], v[160:161], v[170:171]
	v_cvt_pk_bf16_f32 v176, v154, v155
	v_cvt_pk_bf16_f32 v177, v156, v157
	v_cvt_pk_bf16_f32 v178, v158, v159
	v_cvt_pk_bf16_f32 v179, v160, v161
	global_store_dwordx4 v144, v[176:179], s[98:99] offset:256
	v_add_f32_e32 v162, v170, v171
	s_nop 1
	v_add_f32_dpp v163, v162, v162 quad_perm:[1,0,3,2] row_mask:0xf bank_mask:0xf
	s_nop 1
	v_add_f32_dpp v164, v163, v163 quad_perm:[2,3,0,1] row_mask:0xf bank_mask:0xf
	s_mov_b64 exec, vcc
	global_atomic_add_f32 v145, v164, s[10:11] offset:128
	s_mov_b64 exec, s[18:19]
	s_add_u32 s98, s98, 0x8000
	s_addc_u32 s99, s99, 0
	s_waitcnt lgkmcnt(0)
	ds_read_b128 v[146:149], v142
	ds_read_b128 v[150:153], v143
	ds_read_b128 v[154:157], v142 offset:128
	ds_read_b128 v[158:161], v143 offset:128
	s_waitcnt lgkmcnt(0)
	ds_write_b128 v140, v[60:63]
	ds_write_b128 v141, v[56:59]
	ds_write_b128 v140, v[52:55] offset:128
	ds_write_b128 v141, v[48:51] offset:128
	s_waitcnt vmcnt(17)
	v_lshlrev_b32_e32 v162, 16, v212
	v_and_b32_e32 v163, 0xffff0000, v212
	v_lshlrev_b32_e32 v164, 16, v213
	v_and_b32_e32 v165, 0xffff0000, v213
	v_lshlrev_b32_e32 v166, 16, v214
	v_and_b32_e32 v167, 0xffff0000, v214
	v_lshlrev_b32_e32 v168, 16, v215
	v_and_b32_e32 v169, 0xffff0000, v215
	v_pk_add_f32 v[146:147], v[146:147], v[162:163]
	v_pk_add_f32 v[148:149], v[148:149], v[164:165]
	v_pk_add_f32 v[150:151], v[150:151], v[166:167]
	v_pk_add_f32 v[152:153], v[152:153], v[168:169]
	v_pk_mul_f32 v[170:171], v[146:147], v[146:147]
	v_pk_fma_f32 v[170:171], v[148:149], v[148:149], v[170:171]
	v_pk_fma_f32 v[170:171], v[150:151], v[150:151], v[170:171]
	v_pk_fma_f32 v[170:171], v[152:153], v[152:153], v[170:171]
	v_cvt_pk_bf16_f32 v172, v146, v147
	v_cvt_pk_bf16_f32 v173, v148, v149
	v_cvt_pk_bf16_f32 v174, v150, v151
	v_cvt_pk_bf16_f32 v175, v152, v153
	global_store_dwordx4 v144, v[172:175], s[98:99]
	v_lshlrev_b32_e32 v162, 16, v216
	v_and_b32_e32 v163, 0xffff0000, v216
	v_lshlrev_b32_e32 v164, 16, v217
	v_and_b32_e32 v165, 0xffff0000, v217
	v_lshlrev_b32_e32 v166, 16, v218
	v_and_b32_e32 v167, 0xffff0000, v218
	v_lshlrev_b32_e32 v168, 16, v219
	v_and_b32_e32 v169, 0xffff0000, v219
	v_pk_add_f32 v[154:155], v[154:155], v[162:163]
	v_pk_add_f32 v[156:157], v[156:157], v[164:165]
	v_pk_add_f32 v[158:159], v[158:159], v[166:167]
	v_pk_add_f32 v[160:161], v[160:161], v[168:169]
	v_pk_fma_f32 v[170:171], v[154:155], v[154:155], v[170:171]
	v_pk_fma_f32 v[170:171], v[156:157], v[156:157], v[170:171]
	v_pk_fma_f32 v[170:171], v[158:159], v[158:159], v[170:171]
	v_pk_fma_f32 v[170:171], v[160:161], v[160:161], v[170:171]
	v_cvt_pk_bf16_f32 v176, v154, v155
	v_cvt_pk_bf16_f32 v177, v156, v157
	v_cvt_pk_bf16_f32 v178, v158, v159
	v_cvt_pk_bf16_f32 v179, v160, v161
	global_store_dwordx4 v144, v[176:179], s[98:99] offset:256
	v_add_f32_e32 v162, v170, v171
	s_nop 1
	v_add_f32_dpp v163, v162, v162 quad_perm:[1,0,3,2] row_mask:0xf bank_mask:0xf
	s_nop 1
	v_add_f32_dpp v164, v163, v163 quad_perm:[2,3,0,1] row_mask:0xf bank_mask:0xf
	s_mov_b64 exec, vcc
	global_atomic_add_f32 v145, v164, s[10:11] offset:192
	s_mov_b64 exec, s[18:19]
	s_add_u32 s98, s98, 0x28000
	s_addc_u32 s99, s99, 0
	s_waitcnt lgkmcnt(0)
	ds_read_b128 v[146:149], v142
	ds_read_b128 v[150:153], v143
	ds_read_b128 v[154:157], v142 offset:128
	ds_read_b128 v[158:161], v143 offset:128
	s_waitcnt lgkmcnt(0)
	ds_write_b128 v140, v[44:47]
	ds_write_b128 v141, v[40:43]
	ds_write_b128 v140, v[36:39] offset:128
	ds_write_b128 v141, v[32:35] offset:128
	s_waitcnt vmcnt(18)
	v_lshlrev_b32_e32 v162, 16, v220
	v_and_b32_e32 v163, 0xffff0000, v220
	v_lshlrev_b32_e32 v164, 16, v221
	v_and_b32_e32 v165, 0xffff0000, v221
	v_lshlrev_b32_e32 v166, 16, v222
	v_and_b32_e32 v167, 0xffff0000, v222
	v_lshlrev_b32_e32 v168, 16, v223
	v_and_b32_e32 v169, 0xffff0000, v223
	v_pk_add_f32 v[146:147], v[146:147], v[162:163]
	v_pk_add_f32 v[148:149], v[148:149], v[164:165]
	v_pk_add_f32 v[150:151], v[150:151], v[166:167]
	v_pk_add_f32 v[152:153], v[152:153], v[168:169]
	v_pk_mul_f32 v[170:171], v[146:147], v[146:147]
	v_pk_fma_f32 v[170:171], v[148:149], v[148:149], v[170:171]
	v_pk_fma_f32 v[170:171], v[150:151], v[150:151], v[170:171]
	v_pk_fma_f32 v[170:171], v[152:153], v[152:153], v[170:171]
	v_cvt_pk_bf16_f32 v172, v146, v147
	v_cvt_pk_bf16_f32 v173, v148, v149
	v_cvt_pk_bf16_f32 v174, v150, v151
	v_cvt_pk_bf16_f32 v175, v152, v153
	global_store_dwordx4 v144, v[172:175], s[98:99]
	v_lshlrev_b32_e32 v162, 16, v224
	v_and_b32_e32 v163, 0xffff0000, v224
	v_lshlrev_b32_e32 v164, 16, v225
	v_and_b32_e32 v165, 0xffff0000, v225
	v_lshlrev_b32_e32 v166, 16, v226
	v_and_b32_e32 v167, 0xffff0000, v226
	v_lshlrev_b32_e32 v168, 16, v227
	v_and_b32_e32 v169, 0xffff0000, v227
	v_pk_add_f32 v[154:155], v[154:155], v[162:163]
	v_pk_add_f32 v[156:157], v[156:157], v[164:165]
	v_pk_add_f32 v[158:159], v[158:159], v[166:167]
	v_pk_add_f32 v[160:161], v[160:161], v[168:169]
	v_pk_fma_f32 v[170:171], v[154:155], v[154:155], v[170:171]
	v_pk_fma_f32 v[170:171], v[156:157], v[156:157], v[170:171]
	v_pk_fma_f32 v[170:171], v[158:159], v[158:159], v[170:171]
	v_pk_fma_f32 v[170:171], v[160:161], v[160:161], v[170:171]
	v_cvt_pk_bf16_f32 v176, v154, v155
	v_cvt_pk_bf16_f32 v177, v156, v157
	v_cvt_pk_bf16_f32 v178, v158, v159
	v_cvt_pk_bf16_f32 v179, v160, v161
	global_store_dwordx4 v144, v[176:179], s[98:99] offset:256
	v_add_f32_e32 v162, v170, v171
	s_nop 1
	v_add_f32_dpp v163, v162, v162 quad_perm:[1,0,3,2] row_mask:0xf bank_mask:0xf
	s_nop 1
	v_add_f32_dpp v164, v163, v163 quad_perm:[2,3,0,1] row_mask:0xf bank_mask:0xf
	s_mov_b64 exec, vcc
	global_atomic_add_f32 v145, v164, s[10:11] offset:512
	s_mov_b64 exec, s[18:19]
	s_add_u32 s98, s98, 0x8000
	s_addc_u32 s99, s99, 0
	s_waitcnt lgkmcnt(0)
	ds_read_b128 v[146:149], v142
	ds_read_b128 v[150:153], v143
	ds_read_b128 v[154:157], v142 offset:128
	ds_read_b128 v[158:161], v143 offset:128
	s_waitcnt lgkmcnt(0)
	ds_write_b128 v140, v[28:31]
	ds_write_b128 v141, v[24:27]
	ds_write_b128 v140, v[20:23] offset:128
	ds_write_b128 v141, v[16:19] offset:128
	s_waitcnt vmcnt(19)
	v_lshlrev_b32_e32 v162, 16, v228
	v_and_b32_e32 v163, 0xffff0000, v228
	v_lshlrev_b32_e32 v164, 16, v229
	v_and_b32_e32 v165, 0xffff0000, v229
	v_lshlrev_b32_e32 v166, 16, v230
	v_and_b32_e32 v167, 0xffff0000, v230
	v_lshlrev_b32_e32 v168, 16, v231
	v_and_b32_e32 v169, 0xffff0000, v231
	v_pk_add_f32 v[146:147], v[146:147], v[162:163]
	v_pk_add_f32 v[148:149], v[148:149], v[164:165]
	v_pk_add_f32 v[150:151], v[150:151], v[166:167]
	v_pk_add_f32 v[152:153], v[152:153], v[168:169]
	v_pk_mul_f32 v[170:171], v[146:147], v[146:147]
	v_pk_fma_f32 v[170:171], v[148:149], v[148:149], v[170:171]
	v_pk_fma_f32 v[170:171], v[150:151], v[150:151], v[170:171]
	v_pk_fma_f32 v[170:171], v[152:153], v[152:153], v[170:171]
	v_cvt_pk_bf16_f32 v172, v146, v147
	v_cvt_pk_bf16_f32 v173, v148, v149
	v_cvt_pk_bf16_f32 v174, v150, v151
	v_cvt_pk_bf16_f32 v175, v152, v153
	global_store_dwordx4 v144, v[172:175], s[98:99]
	v_lshlrev_b32_e32 v162, 16, v232
	v_and_b32_e32 v163, 0xffff0000, v232
	v_lshlrev_b32_e32 v164, 16, v233
	v_and_b32_e32 v165, 0xffff0000, v233
	v_lshlrev_b32_e32 v166, 16, v234
	v_and_b32_e32 v167, 0xffff0000, v234
	v_lshlrev_b32_e32 v168, 16, v235
	v_and_b32_e32 v169, 0xffff0000, v235
	v_pk_add_f32 v[154:155], v[154:155], v[162:163]
	v_pk_add_f32 v[156:157], v[156:157], v[164:165]
	v_pk_add_f32 v[158:159], v[158:159], v[166:167]
	v_pk_add_f32 v[160:161], v[160:161], v[168:169]
	v_pk_fma_f32 v[170:171], v[154:155], v[154:155], v[170:171]
	v_pk_fma_f32 v[170:171], v[156:157], v[156:157], v[170:171]
	v_pk_fma_f32 v[170:171], v[158:159], v[158:159], v[170:171]
	v_pk_fma_f32 v[170:171], v[160:161], v[160:161], v[170:171]
	v_cvt_pk_bf16_f32 v176, v154, v155
	v_cvt_pk_bf16_f32 v177, v156, v157
	v_cvt_pk_bf16_f32 v178, v158, v159
	v_cvt_pk_bf16_f32 v179, v160, v161
	global_store_dwordx4 v144, v[176:179], s[98:99] offset:256
	v_add_f32_e32 v162, v170, v171
	s_nop 1
	v_add_f32_dpp v163, v162, v162 quad_perm:[1,0,3,2] row_mask:0xf bank_mask:0xf
	s_nop 1
	v_add_f32_dpp v164, v163, v163 quad_perm:[2,3,0,1] row_mask:0xf bank_mask:0xf
	s_mov_b64 exec, vcc
	global_atomic_add_f32 v145, v164, s[10:11] offset:576
	s_mov_b64 exec, s[18:19]
	s_add_u32 s98, s98, 0x8000
	s_addc_u32 s99, s99, 0
	s_waitcnt lgkmcnt(0)
	ds_read_b128 v[146:149], v142
	ds_read_b128 v[150:153], v143
	ds_read_b128 v[154:157], v142 offset:128
	ds_read_b128 v[158:161], v143 offset:128
	s_waitcnt lgkmcnt(0)
	ds_write_b128 v140, v[12:15]
	ds_write_b128 v141, v[8:11]
	ds_write_b128 v140, v[4:7] offset:128
	ds_write_b128 v141, v[0:3] offset:128
	s_waitcnt vmcnt(20)
	v_lshlrev_b32_e32 v162, 16, v236
	v_and_b32_e32 v163, 0xffff0000, v236
	v_lshlrev_b32_e32 v164, 16, v237
	v_and_b32_e32 v165, 0xffff0000, v237
	v_lshlrev_b32_e32 v166, 16, v238
	v_and_b32_e32 v167, 0xffff0000, v238
	v_lshlrev_b32_e32 v168, 16, v239
	v_and_b32_e32 v169, 0xffff0000, v239
	v_pk_add_f32 v[146:147], v[146:147], v[162:163]
	v_pk_add_f32 v[148:149], v[148:149], v[164:165]
	v_pk_add_f32 v[150:151], v[150:151], v[166:167]
	v_pk_add_f32 v[152:153], v[152:153], v[168:169]
	v_pk_mul_f32 v[170:171], v[146:147], v[146:147]
	v_pk_fma_f32 v[170:171], v[148:149], v[148:149], v[170:171]
	v_pk_fma_f32 v[170:171], v[150:151], v[150:151], v[170:171]
	v_pk_fma_f32 v[170:171], v[152:153], v[152:153], v[170:171]
	v_cvt_pk_bf16_f32 v172, v146, v147
	v_cvt_pk_bf16_f32 v173, v148, v149
	v_cvt_pk_bf16_f32 v174, v150, v151
	v_cvt_pk_bf16_f32 v175, v152, v153
	global_store_dwordx4 v144, v[172:175], s[98:99]
	v_lshlrev_b32_e32 v162, 16, v240
	v_and_b32_e32 v163, 0xffff0000, v240
	v_lshlrev_b32_e32 v164, 16, v241
	v_and_b32_e32 v165, 0xffff0000, v241
	v_lshlrev_b32_e32 v166, 16, v242
	v_and_b32_e32 v167, 0xffff0000, v242
	v_lshlrev_b32_e32 v168, 16, v243
	v_and_b32_e32 v169, 0xffff0000, v243
	v_pk_add_f32 v[154:155], v[154:155], v[162:163]
	v_pk_add_f32 v[156:157], v[156:157], v[164:165]
	v_pk_add_f32 v[158:159], v[158:159], v[166:167]
	v_pk_add_f32 v[160:161], v[160:161], v[168:169]
	v_pk_fma_f32 v[170:171], v[154:155], v[154:155], v[170:171]
	v_pk_fma_f32 v[170:171], v[156:157], v[156:157], v[170:171]
	v_pk_fma_f32 v[170:171], v[158:159], v[158:159], v[170:171]
	v_pk_fma_f32 v[170:171], v[160:161], v[160:161], v[170:171]
	v_cvt_pk_bf16_f32 v176, v154, v155
	v_cvt_pk_bf16_f32 v177, v156, v157
	v_cvt_pk_bf16_f32 v178, v158, v159
	v_cvt_pk_bf16_f32 v179, v160, v161
	global_store_dwordx4 v144, v[176:179], s[98:99] offset:256
	v_add_f32_e32 v162, v170, v171
	s_nop 1
	v_add_f32_dpp v163, v162, v162 quad_perm:[1,0,3,2] row_mask:0xf bank_mask:0xf
	s_nop 1
	v_add_f32_dpp v164, v163, v163 quad_perm:[2,3,0,1] row_mask:0xf bank_mask:0xf
	s_mov_b64 exec, vcc
	global_atomic_add_f32 v145, v164, s[10:11] offset:640
	s_mov_b64 exec, s[18:19]
	s_add_u32 s98, s98, 0x8000
	s_addc_u32 s99, s99, 0
	s_waitcnt lgkmcnt(0)
	ds_read_b128 v[146:149], v142
	ds_read_b128 v[150:153], v143
	ds_read_b128 v[154:157], v142 offset:128
	ds_read_b128 v[158:161], v143 offset:128
	s_waitcnt lgkmcnt(0)
	s_waitcnt vmcnt(21)
	v_lshlrev_b32_e32 v162, 16, v244
	v_and_b32_e32 v163, 0xffff0000, v244
	v_lshlrev_b32_e32 v164, 16, v245
	v_and_b32_e32 v165, 0xffff0000, v245
	v_lshlrev_b32_e32 v166, 16, v246
	v_and_b32_e32 v167, 0xffff0000, v246
	v_lshlrev_b32_e32 v168, 16, v247
	v_and_b32_e32 v169, 0xffff0000, v247
	v_pk_add_f32 v[146:147], v[146:147], v[162:163]
	v_pk_add_f32 v[148:149], v[148:149], v[164:165]
	v_pk_add_f32 v[150:151], v[150:151], v[166:167]
	v_pk_add_f32 v[152:153], v[152:153], v[168:169]
	v_pk_mul_f32 v[170:171], v[146:147], v[146:147]
	v_pk_fma_f32 v[170:171], v[148:149], v[148:149], v[170:171]
	v_pk_fma_f32 v[170:171], v[150:151], v[150:151], v[170:171]
	v_pk_fma_f32 v[170:171], v[152:153], v[152:153], v[170:171]
	v_cvt_pk_bf16_f32 v172, v146, v147
	v_cvt_pk_bf16_f32 v173, v148, v149
	v_cvt_pk_bf16_f32 v174, v150, v151
	v_cvt_pk_bf16_f32 v175, v152, v153
	global_store_dwordx4 v144, v[172:175], s[98:99]
	v_lshlrev_b32_e32 v162, 16, v248
	v_and_b32_e32 v163, 0xffff0000, v248
	v_lshlrev_b32_e32 v164, 16, v249
	v_and_b32_e32 v165, 0xffff0000, v249
	v_lshlrev_b32_e32 v166, 16, v250
	v_and_b32_e32 v167, 0xffff0000, v250
	v_lshlrev_b32_e32 v168, 16, v251
	v_and_b32_e32 v169, 0xffff0000, v251
	v_pk_add_f32 v[154:155], v[154:155], v[162:163]
	v_pk_add_f32 v[156:157], v[156:157], v[164:165]
	v_pk_add_f32 v[158:159], v[158:159], v[166:167]
	v_pk_add_f32 v[160:161], v[160:161], v[168:169]
	v_pk_fma_f32 v[170:171], v[154:155], v[154:155], v[170:171]
	v_pk_fma_f32 v[170:171], v[156:157], v[156:157], v[170:171]
	v_pk_fma_f32 v[170:171], v[158:159], v[158:159], v[170:171]
	v_pk_fma_f32 v[170:171], v[160:161], v[160:161], v[170:171]
	v_cvt_pk_bf16_f32 v176, v154, v155
	v_cvt_pk_bf16_f32 v177, v156, v157
	v_cvt_pk_bf16_f32 v178, v158, v159
	v_cvt_pk_bf16_f32 v179, v160, v161
	global_store_dwordx4 v144, v[176:179], s[98:99] offset:256
	v_add_f32_e32 v162, v170, v171
	s_nop 1
	v_add_f32_dpp v163, v162, v162 quad_perm:[1,0,3,2] row_mask:0xf bank_mask:0xf
	s_nop 1
	v_add_f32_dpp v164, v163, v163 quad_perm:[2,3,0,1] row_mask:0xf bank_mask:0xf
	s_mov_b64 exec, vcc
	global_atomic_add_f32 v145, v164, s[10:11] offset:704
	s_mov_b64 exec, s[18:19]
